# speedup vs baseline: 1.0342x; 1.0342x over previous
; template <int NT, int BM, int BN, bool PLAIN, int NSTAGE, bool EPI_LDS>
; __device__ __forceinline__ void gemm_tile(const Params& p, const GemmDesc& g, bf16_t* lds, const int tid) {
;   constexpr int WN = NT / 128;
;   constexpr int WTM = BM / 2, WTN = BN / WN;
;   constexpr int MI = WTM / 16, NI = WTN / 16;
;   constexpr int RP = NT / 8;
;   constexpr int NA = BM / RP, NB = BN / RP;
;   const int lane = tid & 63, wave = tid >> 6;
;   const int wm = wave / WN, wn = wave % WN;
;   const int fr = lane & 15, fq = lane >> 4;
;   const int m0 = g.m0, n0 = g.n0;
;   const int r0 = tid >> 3, c0 = tid & 7;
;   unsigned aoff[PLAIN ? 1 : NA];
;   const char* abase = (const char*)g.A;
;   if (PLAIN) {
;     abase = (const char*)(g.A + (long)m0 * g.lda_lo);
;     aoff[0] = (unsigned)((r0 * (int)g.lda_lo + c0 * 8) * 2);
;   } else {
; #pragma unroll
;     for (int i = 0; i < NA; ++i) {
;       int ra = m0 + r0 + RP * i;
;       int rlo = ra & g.rmask; rlo = rlo < g.rclamp ? rlo : g.rclamp;
;       aoff[i] = (unsigned)(((long)rlo * g.lda_lo + (long)(ra >> g.rshift) * g.lda_hi + c0 * 8) * 2);
;     }
;   }
;   const char* bbase = (const char*)(g.Bt + (long)n0 * g.ldb);
;   const unsigned boff = (unsigned)((r0 * (int)g.ldb + c0 * 8) * 2);
;   const long astepP = (long)RP * g.lda_lo * 2, bstepP = (long)RP * g.ldb * 2;
;   u32x4 ra4[NA], rb4[NB];
;   f32x4 acc[MI][NI];
; #pragma unroll
;   for (int i = 0; i < MI; ++i)
; #pragma unroll
;     for (int j = 0; j < NI; ++j) acc[i][j] = f32x4{0.f, 0.f, 0.f, 0.f};
;   const int nk = g.K >> 6;
;     ...
;   constexpr int STAGE_BYTES = (BM + BN) * 128;
;   char* const ldsb = (char*)lds;
;   const unsigned woff = (unsigned)(((r0 >> 4) * 2 + (c0 >> 2)) * 1024 + (((((r0 & 15) ^ (c0 >> 2)) * 64) + (c0 & 3) * 16) ^ (((r0 & 15) >> 3) << 5)));
;   const unsigned roff = (unsigned)(((fr * 64) + fq * 16) ^ ((fr >> 3) << 5));
;   const int roff1d = (int)((((fr ^ 1) * 64 + fq * 16) ^ ((fr >> 3) << 5))) - (int)roff;
; __device__ __forceinline__ void run_phase(const Params& p, int ph, bf16_t* lds, const int wave0) {
;     ...
;   if (lp == 0 || lp == 4 || lp == 5 || lp == 7 || lp == 8) {
;     const int NT = (lp == 0) ? 40 : (lp == 7 ? 32 : 8);
;     const int ngemm = 64 * NT;
;     const int nsub = (lp == 4) ? 3 : 1;
;     for (int idx = pbid; idx < ngemm; idx += pnb) {
;       const int rnd = idx >> 8, wv = idx & 255;
;       const int xcd = wv & 7, kk = wv >> 3;
.LBB0_883:
	v_readlane_b32 s66, v254, 12
	v_readlane_b32 s67, v254, 13
	s_and_b64 vcc, exec, s[54:55]
	s_cbranch_vccz .LBB0_989
	s_cmp_eq_u32 s39, 7
	s_cselect_b64 s[0:1], -1, 0
	s_and_b64 s[2:3], s[0:1], exec
	s_movk_i32 s2, 0x800
	s_cselect_b32 s6, s2, 0x200
	s_cmp_lg_u32 s39, 0
	s_cselect_b64 s[4:5], -1, 0
	s_and_b64 s[2:3], s[4:5], exec
	s_cselect_b32 s36, s6, 0xa00
	s_cmp_ge_i32 s70, s36
	s_cbranch_scc1 .LBB0_989
	v_ashrrev_i32_e32 v0, 6, v224
	s_cmp_eq_u32 s39, 4
	s_waitcnt vmcnt(12)
	v_lshrrev_b32_e32 v2, 30, v0
	s_cselect_b64 s[6:7], -1, 0
	s_cmp_lg_u32 s39, 4
	v_add_u32_e32 v2, v0, v2
	s_cselect_b64 s[8:9], -1, 0
	s_cmp_lg_u32 s39, 5
	v_ashrrev_i32_e32 v3, 2, v2
	v_and_b32_e32 v2, -4, v2
	v_bfe_u32 v6, v224, 2, 1
	s_mov_b32 s2, 0x3ffffe
	s_cselect_b64 s[10:11], -1, 0
	v_sub_u32_e32 v2, v0, v2
	v_and_or_b32 v0, v0, s2, v6
	s_and_b64 s[2:3], s[0:1], exec
	s_movk_i32 s2, 0x2000
	s_cselect_b32 s80, 0x800, s2
	s_mov_b32 s2, 0x240f4800
	s_cselect_b32 s2, s2, 0x7cf4800
	s_add_u32 s14, s84, s2
	s_addc_u32 s15, s85, 0
	s_and_b64 s[2:3], s[0:1], exec
	s_mov_b32 s2, 0x3880000
	s_cselect_b32 s2, s2, 0x5880000
	v_ashrrev_i32_e32 v178, 3, v224
	v_lshlrev_b32_e32 v7, 4, v224
	s_add_u32 s16, s84, s2
	v_and_b32_e32 v4, 7, v224
	v_bitop3_b32 v6, v178, v6, 15 bitop3:0x6c
	v_and_b32_e32 v7, 48, v7
	s_addc_u32 s17, s85, 0
	v_lshlrev_b32_e32 v179, 3, v4
	v_and_b32_e32 v4, 15, v224
	v_bfe_u32 v5, v224, 4, 2
	v_lshl_or_b32 v6, v6, 6, v7
	v_lshlrev_b32_e32 v7, 2, v178
	s_waitcnt vmcnt(8)
	v_lshlrev_b32_e32 v10, 2, v224
	s_and_b64 s[0:1], s[0:1], exec
	v_and_b32_e32 v7, 32, v7
	v_lshlrev_b32_e32 v8, 6, v4
	v_lshlrev_b32_e32 v9, 4, v5
	v_and_b32_e32 v10, 32, v10
	v_lshlrev_b32_e32 v0, 10, v0
	s_mov_b32 s0, 0x1c0f4800
	v_bitop3_b32 v180, v9, v10, v8 bitop3:0x36
	v_bitop3_b32 v182, v6, v0, v7 bitop3:0xde
	v_lshlrev_b32_e32 v183, 14, v3
	v_lshl_or_b32 v0, v3, 7, v4
	v_lshlrev_b32_e32 v3, 3, v5
	s_cselect_b32 s0, 0x7cf4800, s0
	v_xor_b32_e32 v8, 64, v180
	v_lshlrev_b32_e32 v184, 13, v2
	v_lshl_or_b32 v2, v2, 7, v3
	v_mul_lo_u32 v0, v0, s50
	s_cselect_b32 s37, 32, 0x80
	s_cselect_b32 s38, 9, 8
	s_add_u32 s18, s84, s0
	v_sub_u32_e32 v181, v8, v180
	s_mov_b64 s[12:13], s[80:81]
	s_addc_u32 s19, s85, 0
	s_lshl_b32 s39, s70, 2
	v_add_u32_e32 v185, v2, v0
	v_and_b32_e32 v4, 15, v224
	v_bfe_u32 v5, v224, 4, 2
	v_lshrrev_b32_e32 v6, 3, v4
	v_and_b32_e32 v7, 7, v4
	v_bfe_u32 v8, v4, 1, 2
	v_xor_b32_e32 v8, v8, v5
	v_lshlrev_b32_e32 v8, 4, v8
	v_lshl_or_b32 v8, v7, 7, v8
	v_lshl_or_b32 v8, v6, 10, v8
	v_lshl_or_b32 v180, v6, 6, v8
	v_xor_b32_e32 v8, 64, v180
	v_sub_u32_e32 v181, v8, v180
	s_mov_b32 s40, s70
	s_branch .LBB0_887

; template <int NT, int BM, int BN, bool PLAIN, int NSTAGE, bool EPI_LDS>
; __device__ __forceinline__ void gemm_tile(const Params& p, const GemmDesc& g, bf16_t* lds, const int tid) {
;     ...
;   const char* bbase = (const char*)(g.Bt + (long)n0 * g.ldb);
;   const unsigned boff = (unsigned)((r0 * (int)g.ldb + c0 * 8) * 2);
;   const long astepP = (long)RP * g.lda_lo * 2, bstepP = (long)RP * g.ldb * 2;
;   u32x4 ra4[NA], rb4[NB];
;   f32x4 acc[MI][NI];
; #pragma unroll
;   for (int i = 0; i < MI; ++i)
; #pragma unroll
;     for (int j = 0; j < NI; ++j) acc[i][j] = f32x4{0.f, 0.f, 0.f, 0.f};
;   const int nk = g.K >> 6;
;     ...
;   constexpr int STAGE_BYTES = (BM + BN) * 128;
;   char* const ldsb = (char*)lds;
;   const unsigned woff = (unsigned)(((r0 >> 4) * 2 + (c0 >> 2)) * 1024 + (((((r0 & 15) ^ (c0 >> 2)) * 64) + (c0 & 3) * 16) ^ (((r0 & 15) >> 3) << 5)));
;   const unsigned roff = (unsigned)(((fr * 64) + fq * 16) ^ ((fr >> 3) << 5));
;   const int roff1d = (int)((((fr ^ 1) * 64 + fq * 16) ^ ((fr >> 3) << 5))) - (int)roff;
;     ...
;   } else {
;     GLOAD(0)
;     __syncthreads();
;     LWRITE(0)
;     if (nk > 1) GLOAD(1)
;     __syncthreads();
.LBB0_896:
	v_lshrrev_b32_e32 v0, 6, v224
	v_and_b32_e32 v2, 63, v224
	v_readfirstlane_b32 s57, v0
	v_lshrrev_b32_e32 v3, 3, v2
	v_bfe_u32 v4, v2, 4, 2
	v_and_b32_e32 v5, 3, v2
	v_xor_b32_e32 v4, v4, v5
	v_lshlrev_b32_e32 v4, 4, v4
	v_bfe_u32 v5, v2, 2, 1
	v_lshl_or_b32 v4, v5, 6, v4
	v_xor_b32_e32 v5, 64, v4
	s_cmp_ge_u32 s57, 4
	s_cselect_b32 s58, s26, s52
	s_cselect_b32 s59, s41, s42
	s_cselect_b32 s60, s28, s30
	s_cselect_b32 s61, s29, s31
	s_and_b32 s62, s57, 3
	s_lshl_b32 s62, s62, 6
	s_add_i32 s59, s59, s62
	s_mul_i32 s59, s59, s58
	s_lshl_b32 s58, s58, 1
	s_lshl_b32 s59, s59, 1
	s_add_u32 s60, s60, s59
	s_addc_u32 s61, s61, 0
	v_mul_lo_u32 v3, v3, s58
	s_lshl_b32 s62, s58, 3
	v_add_u32_e32 v162, v3, v4
	v_add3_u32 v163, v3, v5, s62
	s_lshl_b32 s62, s58, 4
	v_add_u32_e32 v164, s62, v162
	v_add_u32_e32 v165, s62, v163
	v_add_u32_e32 v166, s62, v164
	v_add_u32_e32 v167, s62, v165
	v_add_u32_e32 v168, s62, v166
	v_add_u32_e32 v169, s62, v167
	s_lshl_b32 s57, s57, 13
	s_barrier
	s_mov_b32 m0, s57
	s_nop 0
	global_load_lds_dwordx4 v162, s[60:61]
	s_add_u32 m0, m0, 0x400
	s_nop 0
	global_load_lds_dwordx4 v163, s[60:61]
	s_add_u32 m0, m0, 0x400
	s_nop 0
	global_load_lds_dwordx4 v164, s[60:61]
	s_add_u32 m0, m0, 0x400
	s_nop 0
	global_load_lds_dwordx4 v165, s[60:61]
	s_add_u32 m0, m0, 0x400
	s_nop 0
	global_load_lds_dwordx4 v166, s[60:61]
	s_add_u32 m0, m0, 0x400
	s_nop 0
	global_load_lds_dwordx4 v167, s[60:61]
	s_add_u32 m0, m0, 0x400
	s_nop 0
	global_load_lds_dwordx4 v168, s[60:61]
	s_add_u32 m0, m0, 0x400
	s_nop 0
	global_load_lds_dwordx4 v169, s[60:61]
	s_add_u32 s60, s60, 0x80
	s_addc_u32 s61, s61, 0
	s_add_u32 m0, s57, 0x10000
	s_nop 0
	global_load_lds_dwordx4 v162, s[60:61]
	s_add_u32 m0, m0, 0x400
	s_nop 0
	global_load_lds_dwordx4 v163, s[60:61]
	s_add_u32 m0, m0, 0x400
	s_nop 0
	global_load_lds_dwordx4 v164, s[60:61]
	s_add_u32 m0, m0, 0x400
	s_nop 0
	global_load_lds_dwordx4 v165, s[60:61]
	s_add_u32 m0, m0, 0x400
	s_nop 0
	global_load_lds_dwordx4 v166, s[60:61]
	s_add_u32 m0, m0, 0x400
	s_nop 0
	global_load_lds_dwordx4 v167, s[60:61]
	s_add_u32 m0, m0, 0x400
	s_nop 0
	global_load_lds_dwordx4 v168, s[60:61]
	s_add_u32 m0, m0, 0x400
	s_nop 0
	global_load_lds_dwordx4 v169, s[60:61]
	s_add_u32 s60, s60, 0x80
	s_addc_u32 s61, s61, 0
	v_mov_b32_e32 v110, 0
	v_mov_b32_e32 v111, v110
	v_mov_b32_e32 v112, v110
	v_mov_b32_e32 v113, v110
	v_mov_b32_e32 v90, v110
	v_mov_b32_e32 v91, v110
	v_mov_b32_e32 v92, v110
	v_mov_b32_e32 v93, v110
	v_mov_b32_e32 v40, v110
	v_mov_b32_e32 v41, v110
	v_mov_b32_e32 v42, v110
	v_mov_b32_e32 v43, v110
	v_mov_b32_e32 v44, v110
	v_mov_b32_e32 v45, v110
	v_mov_b32_e32 v46, v110
	v_mov_b32_e32 v47, v110
	v_mov_b32_e32 v48, v110
	v_mov_b32_e32 v49, v110
	v_mov_b32_e32 v50, v110
	v_mov_b32_e32 v51, v110
	v_mov_b32_e32 v52, v110
	v_mov_b32_e32 v53, v110
	v_mov_b32_e32 v54, v110
	v_mov_b32_e32 v55, v110
	v_mov_b32_e32 v56, v110
	v_mov_b32_e32 v57, v110
	v_mov_b32_e32 v58, v110
	v_mov_b32_e32 v59, v110
	v_mov_b32_e32 v60, v110
	v_mov_b32_e32 v61, v110
	v_mov_b32_e32 v62, v110
	v_mov_b32_e32 v63, v110
	v_mov_b32_e32 v64, v110
	v_mov_b32_e32 v65, v110
	v_mov_b32_e32 v66, v110
	v_mov_b32_e32 v67, v110
	v_mov_b32_e32 v68, v110
	v_mov_b32_e32 v69, v110
	v_mov_b32_e32 v70, v110
	v_mov_b32_e32 v71, v110
	v_mov_b32_e32 v72, v110
	v_mov_b32_e32 v73, v110
	v_mov_b32_e32 v74, v110
	v_mov_b32_e32 v75, v110
	v_mov_b32_e32 v76, v110
	v_mov_b32_e32 v34, v110
	v_mov_b32_e32 v35, v110
	v_mov_b32_e32 v36, v110
	v_mov_b32_e32 v37, v110
	v_mov_b32_e32 v38, v110
	v_mov_b32_e32 v39, v110
	v_mov_b32_e32 v77, v110
	v_mov_b32_e32 v78, v110
	v_mov_b32_e32 v79, v110
	v_mov_b32_e32 v80, v110
	v_mov_b32_e32 v81, v110
	v_mov_b32_e32 v82, v110
	v_mov_b32_e32 v83, v110
	v_mov_b32_e32 v84, v110
	v_mov_b32_e32 v85, v110
	v_mov_b32_e32 v86, v110
	v_mov_b32_e32 v87, v110
	v_mov_b32_e32 v88, v110
	v_mov_b32_e32 v89, v110
	v_mov_b32_e32 v94, v110
	v_mov_b32_e32 v95, v110
	v_mov_b32_e32 v96, v110
	v_mov_b32_e32 v97, v110
	v_mov_b32_e32 v98, v110
	v_mov_b32_e32 v99, v110
	v_mov_b32_e32 v100, v110
	v_mov_b32_e32 v101, v110
	v_mov_b32_e32 v102, v110
	v_mov_b32_e32 v103, v110
	v_mov_b32_e32 v104, v110
	v_mov_b32_e32 v105, v110
	v_mov_b32_e32 v106, v110
	v_mov_b32_e32 v107, v110
	v_mov_b32_e32 v108, v110
	v_mov_b32_e32 v109, v110
	v_mov_b32_e32 v114, v110
	v_mov_b32_e32 v115, v110
	v_mov_b32_e32 v116, v110
	v_mov_b32_e32 v117, v110
	v_mov_b32_e32 v118, v110
	v_mov_b32_e32 v119, v110
	v_mov_b32_e32 v120, v110
	v_mov_b32_e32 v121, v110
	v_mov_b32_e32 v122, v110
	v_mov_b32_e32 v123, v110
	v_mov_b32_e32 v124, v110
	v_mov_b32_e32 v125, v110
	v_mov_b32_e32 v126, v110
	v_mov_b32_e32 v127, v110
	v_mov_b32_e32 v128, v110
	v_mov_b32_e32 v129, v110
	v_mov_b32_e32 v130, v110
	v_mov_b32_e32 v131, v110
	v_mov_b32_e32 v132, v110
	v_mov_b32_e32 v133, v110
	v_mov_b32_e32 v134, v110
	v_mov_b32_e32 v135, v110
	v_mov_b32_e32 v136, v110
	v_mov_b32_e32 v137, v110
	v_mov_b32_e32 v138, v110
	v_mov_b32_e32 v139, v110
	v_mov_b32_e32 v140, v110
	v_mov_b32_e32 v141, v110
	v_mov_b32_e32 v142, v110
	v_mov_b32_e32 v143, v110
	v_mov_b32_e32 v144, v110
	v_mov_b32_e32 v145, v110
	v_mov_b32_e32 v146, v110
	v_mov_b32_e32 v147, v110
	v_mov_b32_e32 v148, v110
	v_mov_b32_e32 v149, v110
	v_mov_b32_e32 v150, v110
	v_mov_b32_e32 v151, v110
	v_mov_b32_e32 v152, v110
	v_mov_b32_e32 v153, v110
	v_mov_b32_e32 v154, v110
	v_mov_b32_e32 v155, v110
	v_mov_b32_e32 v156, v110
	v_mov_b32_e32 v157, v110
	v_mov_b32_e32 v158, v110
	v_mov_b32_e32 v159, v110
	v_mov_b32_e32 v160, v110
	v_mov_b32_e32 v161, v110
	s_add_i32 s3, s23, -2
	s_mov_b32 s26, 0
	s_mov_b32 s27, s3
	s_waitcnt vmcnt(8)
	s_barrier
	v_add_u32_e32 v19, v180, v184
	v_add_u32_e32 v18, v180, v183
	ds_read_b128 v[2:5], v19 offset:32768
	ds_read_b128 v[6:9], v19 offset:34816
	ds_read_b128 v[10:13], v19 offset:36864
	ds_read_b128 v[14:17], v19 offset:38912
	ds_read_b128 v[202:205], v18
	ds_read_b128 v[206:209], v18 offset:2048
	ds_read_b128 v[226:229], v18 offset:4096
; template <int NT, int BM, int BN, bool PLAIN, int NSTAGE, bool EPI_LDS>
; __device__ __forceinline__ void gemm_tile(const Params& p, const GemmDesc& g, bf16_t* lds, const int tid) {
;     ...
;       for (; kt + 2 < nk; ++kt) {
;         const int cur = kt & 1;
;         COMPUTE_X(cur, 1, 1, kt + 2)
;         __syncthreads();
;       }
.LBB0_897:
	s_and_b32 s28, s26, 0x10000
	v_or_b32_e32 v0, s28, v180
	v_add_u32_e32 v218, v0, v184
	v_add_u32_e32 v0, v0, v183
	s_waitcnt lgkmcnt(2)
	v_mfma_f32_16x16x32_bf16 v[158:161], v[2:5], v[202:205], v[158:161]
	v_add_u32_e32 v218, v218, v181
	s_add_i32 s27, s27, -1
	v_mfma_f32_16x16x32_bf16 v[154:157], v[6:9], v[202:205], v[154:157]
	s_add_i32 s26, s26, 0x10000
	v_mfma_f32_16x16x32_bf16 v[150:153], v[10:13], v[202:205], v[150:153]
	v_mfma_f32_16x16x32_bf16 v[146:149], v[14:17], v[202:205], v[146:149]
	ds_read_b128 v[202:205], v0 offset:6144
	s_waitcnt lgkmcnt(2)
	v_mfma_f32_16x16x32_bf16 v[142:145], v[2:5], v[206:209], v[142:145]
	v_mfma_f32_16x16x32_bf16 v[138:141], v[6:9], v[206:209], v[138:141]
	v_mfma_f32_16x16x32_bf16 v[134:137], v[10:13], v[206:209], v[134:137]
	v_mfma_f32_16x16x32_bf16 v[130:133], v[14:17], v[206:209], v[130:133]
	ds_read_b128 v[206:209], v0 offset:8192
	s_waitcnt lgkmcnt(2)
	v_mfma_f32_16x16x32_bf16 v[126:129], v[2:5], v[226:229], v[126:129]
	v_mfma_f32_16x16x32_bf16 v[122:125], v[6:9], v[226:229], v[122:125]
	v_mfma_f32_16x16x32_bf16 v[118:121], v[10:13], v[226:229], v[118:121]
	v_mfma_f32_16x16x32_bf16 v[114:117], v[14:17], v[226:229], v[114:117]
	ds_read_b128 v[226:229], v0 offset:10240
	s_waitcnt lgkmcnt(2)
	v_mfma_f32_16x16x32_bf16 v[106:109], v[2:5], v[202:205], v[106:109]
	v_mfma_f32_16x16x32_bf16 v[102:105], v[6:9], v[202:205], v[102:105]
	v_mfma_f32_16x16x32_bf16 v[98:101], v[10:13], v[202:205], v[98:101]
	v_mfma_f32_16x16x32_bf16 v[94:97], v[14:17], v[202:205], v[94:97]
	ds_read_b128 v[202:205], v0 offset:12288
	ds_read_b128 v[230:233], v218 offset:32768
	s_waitcnt lgkmcnt(3)
	v_mfma_f32_16x16x32_bf16 v[86:89], v[2:5], v[206:209], v[86:89]
	v_mfma_f32_16x16x32_bf16 v[82:85], v[6:9], v[206:209], v[82:85]
	v_mfma_f32_16x16x32_bf16 v[78:81], v[10:13], v[206:209], v[78:81]
	v_mfma_f32_16x16x32_bf16 v[74:77], v[14:17], v[206:209], v[74:77]
	ds_read_b128 v[206:209], v0 offset:14336
	ds_read_b128 v[234:237], v218 offset:34816
	v_add_u32_e32 v0, v0, v181
	s_waitcnt lgkmcnt(4)
	v_mfma_f32_16x16x32_bf16 v[70:73], v[2:5], v[226:229], v[70:73]
	v_mfma_f32_16x16x32_bf16 v[66:69], v[6:9], v[226:229], v[66:69]
	v_mfma_f32_16x16x32_bf16 v[62:65], v[10:13], v[226:229], v[62:65]
	v_mfma_f32_16x16x32_bf16 v[58:61], v[14:17], v[226:229], v[58:61]
	ds_read_b128 v[226:229], v0 offset:0
	ds_read_b128 v[238:241], v218 offset:36864
	s_waitcnt lgkmcnt(5)
	v_mfma_f32_16x16x32_bf16 v[54:57], v[2:5], v[202:205], v[54:57]
	v_mfma_f32_16x16x32_bf16 v[50:53], v[6:9], v[202:205], v[50:53]
	v_mfma_f32_16x16x32_bf16 v[46:49], v[10:13], v[202:205], v[46:49]
	v_mfma_f32_16x16x32_bf16 v[42:45], v[14:17], v[202:205], v[42:45]
	ds_read_b128 v[202:205], v0 offset:2048
	ds_read_b128 v[242:245], v218 offset:38912
	s_waitcnt lgkmcnt(5)
	v_mfma_f32_16x16x32_bf16 v[38:41], v[2:5], v[206:209], v[38:41]
	v_mfma_f32_16x16x32_bf16 v[34:37], v[6:9], v[206:209], v[34:37]
	v_mfma_f32_16x16x32_bf16 v[90:93], v[10:13], v[206:209], v[90:93]
	v_mfma_f32_16x16x32_bf16 v[110:113], v[14:17], v[206:209], v[110:113]
	ds_read_b128 v[186:189], v0 offset:4096
	s_waitcnt lgkmcnt(4)
	v_mfma_f32_16x16x32_bf16 v[158:161], v[230:233], v[226:229], v[158:161]
	v_mfma_f32_16x16x32_bf16 v[154:157], v[234:237], v[226:229], v[154:157]
	s_waitcnt lgkmcnt(3)
	v_mfma_f32_16x16x32_bf16 v[150:153], v[238:241], v[226:229], v[150:153]
	s_waitcnt lgkmcnt(1)
	v_mfma_f32_16x16x32_bf16 v[146:149], v[242:245], v[226:229], v[146:149]
	ds_read_b128 v[190:193], v0 offset:6144
	v_mfma_f32_16x16x32_bf16 v[142:145], v[230:233], v[202:205], v[142:145]
	v_mfma_f32_16x16x32_bf16 v[138:141], v[234:237], v[202:205], v[138:141]
	v_mfma_f32_16x16x32_bf16 v[134:137], v[238:241], v[202:205], v[134:137]
	v_mfma_f32_16x16x32_bf16 v[130:133], v[242:245], v[202:205], v[130:133]
	ds_read_b128 v[194:197], v0 offset:8192
	s_waitcnt lgkmcnt(2)
	v_mfma_f32_16x16x32_bf16 v[126:129], v[230:233], v[186:189], v[126:129]
	v_mfma_f32_16x16x32_bf16 v[122:125], v[234:237], v[186:189], v[122:125]
	v_mfma_f32_16x16x32_bf16 v[118:121], v[238:241], v[186:189], v[118:121]
	v_mfma_f32_16x16x32_bf16 v[114:117], v[242:245], v[186:189], v[114:117]
	ds_read_b128 v[186:189], v0 offset:10240
	s_waitcnt lgkmcnt(2)
	v_mfma_f32_16x16x32_bf16 v[106:109], v[230:233], v[190:193], v[106:109]
	v_mfma_f32_16x16x32_bf16 v[102:105], v[234:237], v[190:193], v[102:105]
	v_mfma_f32_16x16x32_bf16 v[98:101], v[238:241], v[190:193], v[98:101]
	v_mfma_f32_16x16x32_bf16 v[94:97], v[242:245], v[190:193], v[94:97]
	ds_read_b128 v[190:193], v0 offset:12288
	s_waitcnt lgkmcnt(2)
	v_mfma_f32_16x16x32_bf16 v[86:89], v[230:233], v[194:197], v[86:89]
	v_mfma_f32_16x16x32_bf16 v[82:85], v[234:237], v[194:197], v[82:85]
	v_mfma_f32_16x16x32_bf16 v[78:81], v[238:241], v[194:197], v[78:81]
	v_mfma_f32_16x16x32_bf16 v[74:77], v[242:245], v[194:197], v[74:77]
	ds_read_b128 v[194:197], v0 offset:14336
	s_waitcnt vmcnt(0) lgkmcnt(0)
	s_barrier
; template <int NT, int BM, int BN, bool PLAIN, int NSTAGE, bool EPI_LDS>
; __device__ __forceinline__ void gemm_tile(const Params& p, const GemmDesc& g, bf16_t* lds, const int tid) {
;     ...
;       for (; kt + 2 < nk; ++kt) {
;         const int cur = kt & 1;
;         COMPUTE_X(cur, 1, 1, kt + 2)
;         __syncthreads();
;       }
;       if (kt + 1 < nk) {
;         const int cur = kt & 1;
;         COMPUTE_X(cur, 1, 0, 0)
;         __syncthreads();
;         ++kt;
;       }
	s_xor_b32 s29, s28, 0x10000
	v_or_b32_e32 v18, s29, v180
	v_add_u32_e32 v19, v18, v184
	v_add_u32_e32 v18, v18, v183
	ds_read_b128 v[2:5], v19 offset:32768
	ds_read_b128 v[6:9], v19 offset:34816
	ds_read_b128 v[10:13], v19 offset:36864
	ds_read_b128 v[14:17], v19 offset:38912
	ds_read_b128 v[202:205], v18
	ds_read_b128 v[206:209], v18 offset:2048
	ds_read_b128 v[226:229], v18 offset:4096
	s_add_u32 m0, s28, s57
	v_mfma_f32_16x16x32_bf16 v[70:73], v[230:233], v[186:189], v[70:73]
	global_load_lds_dwordx4 v162, s[60:61]
	s_add_u32 m0, m0, 0x400
	v_mfma_f32_16x16x32_bf16 v[66:69], v[234:237], v[186:189], v[66:69]
	global_load_lds_dwordx4 v163, s[60:61]
	s_add_u32 m0, m0, 0x400
	v_mfma_f32_16x16x32_bf16 v[62:65], v[238:241], v[186:189], v[62:65]
	global_load_lds_dwordx4 v164, s[60:61]
	s_add_u32 m0, m0, 0x400
	v_mfma_f32_16x16x32_bf16 v[58:61], v[242:245], v[186:189], v[58:61]
	global_load_lds_dwordx4 v165, s[60:61]
	s_add_u32 m0, m0, 0x400
	v_mfma_f32_16x16x32_bf16 v[54:57], v[230:233], v[190:193], v[54:57]
	global_load_lds_dwordx4 v166, s[60:61]
	s_add_u32 m0, m0, 0x400
	v_mfma_f32_16x16x32_bf16 v[50:53], v[234:237], v[190:193], v[50:53]
	global_load_lds_dwordx4 v167, s[60:61]
	s_add_u32 m0, m0, 0x400
	v_mfma_f32_16x16x32_bf16 v[46:49], v[238:241], v[190:193], v[46:49]
	global_load_lds_dwordx4 v168, s[60:61]
	s_add_u32 m0, m0, 0x400
	v_mfma_f32_16x16x32_bf16 v[42:45], v[242:245], v[190:193], v[42:45]
	global_load_lds_dwordx4 v169, s[60:61]
	s_add_u32 s60, s60, 0x80
	s_addc_u32 s61, s61, 0
	v_mfma_f32_16x16x32_bf16 v[38:41], v[230:233], v[194:197], v[38:41]
	v_mfma_f32_16x16x32_bf16 v[34:37], v[234:237], v[194:197], v[34:37]
	v_mfma_f32_16x16x32_bf16 v[90:93], v[238:241], v[194:197], v[90:93]
	v_mfma_f32_16x16x32_bf16 v[110:113], v[242:245], v[194:197], v[110:113]
	s_cmp_lg_u32 s27, 0
	s_cbranch_scc1 .LBB0_897
	s_lshl_b32 s3, s3, 16
	s_and_b32 s3, s3, 0x10000
	v_or_b32_e32 v0, s3, v180
	v_add_u32_e32 v198, v0, v184
	ds_read_b128 v[162:165], v198 offset:32768
	ds_read_b128 v[166:169], v198 offset:34816
	ds_read_b128 v[170:173], v198 offset:36864
	ds_read_b128 v[186:189], v198 offset:38912
	v_add_u32_e32 v0, v0, v183
	ds_read_b128 v[174:177], v0
	ds_read_b128 v[190:193], v0 offset:2048
	ds_read_b128 v[194:197], v0 offset:4096
	s_waitcnt lgkmcnt(2)
	v_mfma_f32_16x16x32_bf16 v[30:33], v[162:165], v[174:177], v[158:161]
	s_not_b32 s3, s23
	s_lshl_b32 s3, s3, 16
	s_and_b32 s3, s3, 0x10000
	v_mfma_f32_16x16x32_bf16 v[154:157], v[166:169], v[174:177], v[154:157]
	s_cmp_lg_u32 s56, 9
	s_cselect_b64 s[26:27], -1, 0
	s_mov_b32 s24, s41
	v_mfma_f32_16x16x32_bf16 v[150:153], v[170:173], v[174:177], v[150:153]
	s_mov_b32 s23, s42
	s_mov_b64 s[28:29], -1
	s_and_b64 vcc, exec, s[26:27]
	v_mfma_f32_16x16x32_bf16 v[146:149], v[186:189], v[174:177], v[146:149]
	ds_read_b128 v[158:161], v0 offset:6144
	v_add_u32_e32 v174, v198, v181
	s_waitcnt lgkmcnt(2)
	v_mfma_f32_16x16x32_bf16 v[26:29], v[162:165], v[190:193], v[142:145]
	v_mfma_f32_16x16x32_bf16 v[138:141], v[166:169], v[190:193], v[138:141]
	v_mfma_f32_16x16x32_bf16 v[134:137], v[170:173], v[190:193], v[134:137]
	v_mfma_f32_16x16x32_bf16 v[130:133], v[186:189], v[190:193], v[130:133]
	ds_read_b128 v[142:145], v0 offset:8192
	s_waitcnt lgkmcnt(2)
	v_mfma_f32_16x16x32_bf16 v[22:25], v[162:165], v[194:197], v[126:129]
	v_mfma_f32_16x16x32_bf16 v[122:125], v[166:169], v[194:197], v[122:125]
	v_mfma_f32_16x16x32_bf16 v[118:121], v[170:173], v[194:197], v[118:121]
	v_mfma_f32_16x16x32_bf16 v[114:117], v[186:189], v[194:197], v[114:117]
	ds_read_b128 v[126:129], v0 offset:10240
	s_waitcnt lgkmcnt(2)
	v_mfma_f32_16x16x32_bf16 v[18:21], v[162:165], v[158:161], v[106:109]
	v_mfma_f32_16x16x32_bf16 v[102:105], v[166:169], v[158:161], v[102:105]
	v_mfma_f32_16x16x32_bf16 v[98:101], v[170:173], v[158:161], v[98:101]
	v_mfma_f32_16x16x32_bf16 v[94:97], v[186:189], v[158:161], v[94:97]
	ds_read_b128 v[106:109], v0 offset:12288
	ds_read_b128 v[158:161], v174 offset:32768
	s_waitcnt lgkmcnt(3)
	v_mfma_f32_16x16x32_bf16 v[14:17], v[162:165], v[142:145], v[86:89]
	v_mfma_f32_16x16x32_bf16 v[82:85], v[166:169], v[142:145], v[82:85]
	v_mfma_f32_16x16x32_bf16 v[78:81], v[170:173], v[142:145], v[78:81]
	v_mfma_f32_16x16x32_bf16 v[74:77], v[186:189], v[142:145], v[74:77]
	ds_read_b128 v[86:89], v0 offset:14336
	ds_read_b128 v[142:145], v174 offset:34816
	v_add_u32_e32 v0, v0, v181
	s_waitcnt lgkmcnt(4)
	v_mfma_f32_16x16x32_bf16 v[10:13], v[162:165], v[126:129], v[70:73]
	v_mfma_f32_16x16x32_bf16 v[66:69], v[166:169], v[126:129], v[66:69]
	v_mfma_f32_16x16x32_bf16 v[62:65], v[170:173], v[126:129], v[62:65]
	v_mfma_f32_16x16x32_bf16 v[58:61], v[186:189], v[126:129], v[58:61]
	ds_read_b128 v[70:73], v0 offset:0
	ds_read_b128 v[126:129], v174 offset:36864
	s_waitcnt lgkmcnt(5)
	v_mfma_f32_16x16x32_bf16 v[6:9], v[162:165], v[106:109], v[54:57]
	v_mfma_f32_16x16x32_bf16 v[50:53], v[166:169], v[106:109], v[50:53]
	v_mfma_f32_16x16x32_bf16 v[46:49], v[170:173], v[106:109], v[46:49]
	v_mfma_f32_16x16x32_bf16 v[42:45], v[186:189], v[106:109], v[42:45]
	ds_read_b128 v[106:109], v174 offset:38912
	ds_read_b128 v[54:57], v0 offset:2048
	s_waitcnt lgkmcnt(5)
	v_mfma_f32_16x16x32_bf16 v[2:5], v[162:165], v[86:89], v[38:41]
	v_mfma_f32_16x16x32_bf16 v[34:37], v[166:169], v[86:89], v[34:37]
	v_mfma_f32_16x16x32_bf16 v[38:41], v[170:173], v[86:89], v[90:93]
	v_mfma_f32_16x16x32_bf16 v[86:89], v[186:189], v[86:89], v[110:113]
	s_nop 1
	ds_read_b128 v[90:93], v0 offset:4096
	s_waitcnt lgkmcnt(4)
	v_mfma_f32_16x16x32_bf16 v[30:33], v[158:161], v[70:73], v[30:33]
	v_mfma_f32_16x16x32_bf16 v[110:113], v[142:145], v[70:73], v[154:157]
	s_waitcnt lgkmcnt(3)
; template <int NT, int BM, int BN, bool PLAIN, int NSTAGE, bool EPI_LDS>
; __device__ __forceinline__ void gemm_tile(const Params& p, const GemmDesc& g, bf16_t* lds, const int tid) {
;     ...
;       if (kt + 1 < nk) {
;         const int cur = kt & 1;
;         COMPUTE_X(cur, 1, 0, 0)
;         __syncthreads();
;         ++kt;
;       }
	v_mfma_f32_16x16x32_bf16 v[150:153], v[126:129], v[70:73], v[150:153]
	s_waitcnt lgkmcnt(2)
	v_mfma_f32_16x16x32_bf16 v[70:73], v[106:109], v[70:73], v[146:149]
	s_nop 2
	ds_read_b128 v[146:149], v0 offset:6144
	s_waitcnt lgkmcnt(2)
	v_mfma_f32_16x16x32_bf16 v[26:29], v[158:161], v[54:57], v[26:29]
	v_mfma_f32_16x16x32_bf16 v[138:141], v[142:145], v[54:57], v[138:141]
	v_mfma_f32_16x16x32_bf16 v[134:137], v[126:129], v[54:57], v[134:137]
	v_mfma_f32_16x16x32_bf16 v[54:57], v[106:109], v[54:57], v[130:133]
	s_nop 2
	ds_read_b128 v[130:133], v0 offset:8192
	s_waitcnt lgkmcnt(2)
	v_mfma_f32_16x16x32_bf16 v[22:25], v[158:161], v[90:93], v[22:25]
	v_mfma_f32_16x16x32_bf16 v[122:125], v[142:145], v[90:93], v[122:125]
	v_mfma_f32_16x16x32_bf16 v[118:121], v[126:129], v[90:93], v[118:121]
	v_mfma_f32_16x16x32_bf16 v[90:93], v[106:109], v[90:93], v[114:117]
	s_nop 2
	ds_read_b128 v[114:117], v0 offset:10240
	s_waitcnt lgkmcnt(2)
	v_mfma_f32_16x16x32_bf16 v[18:21], v[158:161], v[146:149], v[18:21]
	v_mfma_f32_16x16x32_bf16 v[102:105], v[142:145], v[146:149], v[102:105]
	v_mfma_f32_16x16x32_bf16 v[98:101], v[126:129], v[146:149], v[98:101]
	v_mfma_f32_16x16x32_bf16 v[94:97], v[106:109], v[146:149], v[94:97]
	ds_read_b128 v[146:149], v0 offset:12288
	s_waitcnt lgkmcnt(2)
	v_mfma_f32_16x16x32_bf16 v[14:17], v[158:161], v[130:133], v[14:17]
	v_mfma_f32_16x16x32_bf16 v[82:85], v[142:145], v[130:133], v[82:85]
	v_mfma_f32_16x16x32_bf16 v[78:81], v[126:129], v[130:133], v[78:81]
	v_mfma_f32_16x16x32_bf16 v[74:77], v[106:109], v[130:133], v[74:77]
	ds_read_b128 v[130:133], v0 offset:14336
	v_or_b32_e32 v0, s3, v180
	v_add_u32_e32 v186, v0, v184
	s_waitcnt lgkmcnt(2)
	v_mfma_f32_16x16x32_bf16 v[10:13], v[158:161], v[114:117], v[10:13]
	s_waitcnt vmcnt(0) lgkmcnt(0)
	s_barrier
; template <int NT, int BM, int BN, bool PLAIN, int NSTAGE, bool EPI_LDS>
; __device__ __forceinline__ void gemm_tile(const Params& p, const GemmDesc& g, bf16_t* lds, const int tid) {
;     ...
;       {
;         const int cur = kt & 1;
;         COMPUTE_X(cur, 0, 0, 0)
;         __syncthreads();
;       }
;     } else {
;       for (int kt = 0; kt < nk; ++kt) {
;         const int cur = kt & 1;
;         if (kt + 1 < nk) {
;           LWRITE(cur ^ 1)
;           if (kt + 2 < nk) GLOAD(kt + 2)
;         }
;         __builtin_amdgcn_sched_barrier(0);
;         COMPUTE(cur)
;         __syncthreads();
;       }
;     }
;   }
;     ...
;   int m0e = m0, n0e = n0;
;   asm volatile("" : "+s"(m0e), "+s"(n0e));
;   if (EPI_LDS) {
;     constexpr int CST = BN + 16;
;     bf16_t* ct = lds;
;     const bool relu2 = (g.epi == E_RELU2);
; #pragma unroll
;     for (int mi = 0; mi < MI; ++mi)
; #pragma unroll
;       for (int ni = 0; ni < NI; ++ni) {
;         f32x4 v = acc[mi][ni];
;         if (relu2) {
; #pragma unroll
;           for (int j = 0; j < 4; ++j) { const float r = fmaxf(v[j], 0.f); v[j] = r * r; }
;         }
;         u32x2 w;
;         w[0] = pack2(v[0], v[1]);
;         w[1] = pack2(v[2], v[3]);
;         *(u32x2*)(ct + (wm * WTM + mi * 16 + fr) * CST + wn * WTN + ni * 16 + fq * 4) = w;
;       }
	v_mfma_f32_16x16x32_bf16 v[66:69], v[142:145], v[114:117], v[66:69]
	v_add_u32_e32 v0, v0, v183
	v_mfma_f32_16x16x32_bf16 v[62:65], v[126:129], v[114:117], v[62:65]
	v_mfma_f32_16x16x32_bf16 v[58:61], v[106:109], v[114:117], v[58:61]
	v_mfma_f32_16x16x32_bf16 v[6:9], v[158:161], v[146:149], v[6:9]
	v_mfma_f32_16x16x32_bf16 v[50:53], v[142:145], v[146:149], v[50:53]
	v_mfma_f32_16x16x32_bf16 v[46:49], v[126:129], v[146:149], v[46:49]
	v_mfma_f32_16x16x32_bf16 v[42:45], v[106:109], v[146:149], v[42:45]
	v_mfma_f32_16x16x32_bf16 v[2:5], v[158:161], v[130:133], v[2:5]
	v_mfma_f32_16x16x32_bf16 v[34:37], v[142:145], v[130:133], v[34:37]
	v_mfma_f32_16x16x32_bf16 v[38:41], v[126:129], v[130:133], v[38:41]
	v_mfma_f32_16x16x32_bf16 v[86:89], v[106:109], v[130:133], v[86:89]
	ds_read_b128 v[106:109], v186 offset:32768
	ds_read_b128 v[114:117], v186 offset:34816
	ds_read_b128 v[130:133], v186 offset:36864
	ds_read_b128 v[142:145], v186 offset:38912
	ds_read_b128 v[126:129], v0
	ds_read_b128 v[146:149], v0 offset:2048
	ds_read_b128 v[154:157], v0 offset:4096
	s_waitcnt lgkmcnt(2)
	v_mfma_f32_16x16x32_bf16 v[30:33], v[106:109], v[126:129], v[30:33]
	v_mfma_f32_16x16x32_bf16 v[110:113], v[114:117], v[126:129], v[110:113]
	v_mfma_f32_16x16x32_bf16 v[150:153], v[130:133], v[126:129], v[150:153]
	v_mfma_f32_16x16x32_bf16 v[70:73], v[142:145], v[126:129], v[70:73]
	ds_read_b128 v[126:129], v0 offset:6144
	s_waitcnt lgkmcnt(2)
	v_mfma_f32_16x16x32_bf16 v[26:29], v[106:109], v[146:149], v[26:29]
	v_mfma_f32_16x16x32_bf16 v[138:141], v[114:117], v[146:149], v[138:141]
	v_mfma_f32_16x16x32_bf16 v[134:137], v[130:133], v[146:149], v[134:137]
	v_mfma_f32_16x16x32_bf16 v[54:57], v[142:145], v[146:149], v[54:57]
	ds_read_b128 v[146:149], v0 offset:8192
	s_waitcnt lgkmcnt(2)
	v_mfma_f32_16x16x32_bf16 v[22:25], v[106:109], v[154:157], v[22:25]
	v_mfma_f32_16x16x32_bf16 v[158:161], v[114:117], v[154:157], v[122:125]
	v_mfma_f32_16x16x32_bf16 v[162:165], v[130:133], v[154:157], v[118:121]
	v_mfma_f32_16x16x32_bf16 v[154:157], v[142:145], v[154:157], v[90:93]
	s_nop 2
	ds_read_b128 v[90:93], v0 offset:10240
	s_waitcnt lgkmcnt(2)
	v_mfma_f32_16x16x32_bf16 v[18:21], v[106:109], v[126:129], v[18:21]
	v_mfma_f32_16x16x32_bf16 v[166:169], v[114:117], v[126:129], v[102:105]
	v_mfma_f32_16x16x32_bf16 v[170:173], v[130:133], v[126:129], v[98:101]
	v_mfma_f32_16x16x32_bf16 v[174:177], v[142:145], v[126:129], v[94:97]
	s_nop 1
	v_add_u32_e32 v98, v186, v181
	ds_read_b128 v[186:189], v98 offset:32768
	ds_read_b128 v[94:97], v0 offset:12288
	s_waitcnt lgkmcnt(3)
	v_mfma_f32_16x16x32_bf16 v[14:17], v[106:109], v[146:149], v[14:17]
	v_mfma_f32_16x16x32_bf16 v[190:193], v[114:117], v[146:149], v[82:85]
	v_mfma_f32_16x16x32_bf16 v[194:197], v[130:133], v[146:149], v[78:81]
	v_mfma_f32_16x16x32_bf16 v[146:149], v[142:145], v[146:149], v[74:77]
	ds_read_b128 v[198:201], v98 offset:34816
	s_nop 1
	ds_read_b128 v[74:77], v0 offset:14336
	v_add_u32_e32 v0, v0, v181
	s_waitcnt lgkmcnt(4)
	v_mfma_f32_16x16x32_bf16 v[10:13], v[106:109], v[90:93], v[10:13]
	v_mfma_f32_16x16x32_bf16 v[202:205], v[114:117], v[90:93], v[66:69]
	v_mfma_f32_16x16x32_bf16 v[206:209], v[130:133], v[90:93], v[62:65]
	v_mfma_f32_16x16x32_bf16 v[226:229], v[142:145], v[90:93], v[58:61]
	ds_read_b128 v[230:233], v98 offset:36864
	s_nop 1
	ds_read_b128 v[58:61], v0 offset:0
	s_waitcnt lgkmcnt(4)
	v_mfma_f32_16x16x32_bf16 v[6:9], v[106:109], v[94:97], v[6:9]
	v_mfma_f32_16x16x32_bf16 v[234:237], v[114:117], v[94:97], v[50:53]
	v_mfma_f32_16x16x32_bf16 v[238:241], v[130:133], v[94:97], v[46:49]
	v_mfma_f32_16x16x32_bf16 v[242:245], v[142:145], v[94:97], v[42:45]
	ds_read_b128 v[246:249], v98 offset:38912
	s_nop 1
	ds_read_b128 v[42:45], v0 offset:2048
	s_waitcnt lgkmcnt(4)
	v_mfma_f32_16x16x32_bf16 v[2:5], v[106:109], v[74:77], v[2:5]
	v_mfma_f32_16x16x32_bf16 v[218:221], v[114:117], v[74:77], v[34:37]
	v_mfma_f32_16x16x32_bf16 v[130:133], v[130:133], v[74:77], v[38:41]
	v_mfma_f32_16x16x32_bf16 v[142:145], v[142:145], v[74:77], v[86:89]
	s_nop 0
	ds_read_b128 v[34:37], v0 offset:4096
	s_waitcnt lgkmcnt(3)
	v_mfma_f32_16x16x32_bf16 v[126:129], v[186:189], v[58:61], v[30:33]
	v_mfma_f32_16x16x32_bf16 v[122:125], v[198:201], v[58:61], v[110:113]
	v_mfma_f32_16x16x32_bf16 v[118:121], v[230:233], v[58:61], v[150:153]
	s_waitcnt lgkmcnt(2)
	v_mfma_f32_16x16x32_bf16 v[114:117], v[246:249], v[58:61], v[70:73]
	ds_read_b128 v[30:33], v0 offset:6144
	s_waitcnt lgkmcnt(2)
	v_mfma_f32_16x16x32_bf16 v[110:113], v[186:189], v[42:45], v[26:29]
	v_mfma_f32_16x16x32_bf16 v[106:109], v[198:201], v[42:45], v[138:141]
	v_mfma_f32_16x16x32_bf16 v[102:105], v[230:233], v[42:45], v[134:137]
	v_mfma_f32_16x16x32_bf16 v[98:101], v[246:249], v[42:45], v[54:57]
	ds_read_b128 v[26:29], v0 offset:8192
	s_waitcnt lgkmcnt(2)
	v_mfma_f32_16x16x32_bf16 v[94:97], v[186:189], v[34:37], v[22:25]
	v_mfma_f32_16x16x32_bf16 v[90:93], v[198:201], v[34:37], v[158:161]
	v_mfma_f32_16x16x32_bf16 v[86:89], v[230:233], v[34:37], v[162:165]
	v_mfma_f32_16x16x32_bf16 v[82:85], v[246:249], v[34:37], v[154:157]
	ds_read_b128 v[22:25], v0 offset:10240
	s_waitcnt lgkmcnt(2)
	v_mfma_f32_16x16x32_bf16 v[78:81], v[186:189], v[30:33], v[18:21]
	v_mfma_f32_16x16x32_bf16 v[74:77], v[198:201], v[30:33], v[166:169]
	v_mfma_f32_16x16x32_bf16 v[70:73], v[230:233], v[30:33], v[170:173]
	v_mfma_f32_16x16x32_bf16 v[66:69], v[246:249], v[30:33], v[174:177]
	ds_read_b128 v[18:21], v0 offset:12288
	s_waitcnt lgkmcnt(2)
	v_mfma_f32_16x16x32_bf16 v[62:65], v[186:189], v[26:29], v[14:17]
	v_mfma_f32_16x16x32_bf16 v[58:61], v[198:201], v[26:29], v[190:193]
	v_mfma_f32_16x16x32_bf16 v[54:57], v[230:233], v[26:29], v[194:197]
	v_mfma_f32_16x16x32_bf16 v[50:53], v[246:249], v[26:29], v[146:149]
	ds_read_b128 v[134:137], v0 offset:14336
	s_waitcnt lgkmcnt(0)
	s_barrier
	v_mfma_f32_16x16x32_bf16 v[46:49], v[186:189], v[22:25], v[10:13]
	v_mfma_f32_16x16x32_bf16 v[42:45], v[198:201], v[22:25], v[202:205]
	v_mfma_f32_16x16x32_bf16 v[38:41], v[230:233], v[22:25], v[206:209]
	v_mfma_f32_16x16x32_bf16 v[34:37], v[246:249], v[22:25], v[226:229]
	v_mfma_f32_16x16x32_bf16 v[30:33], v[186:189], v[18:21], v[6:9]
	v_mfma_f32_16x16x32_bf16 v[26:29], v[198:201], v[18:21], v[234:237]
	v_mfma_f32_16x16x32_bf16 v[22:25], v[230:233], v[18:21], v[238:241]
	v_mfma_f32_16x16x32_bf16 v[18:21], v[246:249], v[18:21], v[242:245]
	v_mfma_f32_16x16x32_bf16 v[14:17], v[186:189], v[134:137], v[2:5]
	v_mfma_f32_16x16x32_bf16 v[10:13], v[198:201], v[134:137], v[218:221]
	v_mfma_f32_16x16x32_bf16 v[2:5], v[230:233], v[134:137], v[130:133]
	v_mfma_f32_16x16x32_bf16 v[6:9], v[246:249], v[134:137], v[142:145]
	s_cbranch_vccz .LBB0_900
	s_nop 0
	v_cvt_pk_bf16_f32 v130, v126, v127
	v_cvt_pk_bf16_f32 v131, v128, v129
	s_mov_b64 s[28:29], 0

; __device__ __forceinline__ float sigmoid_f(float x) { return 1.f / (1.f + __expf(-x)); }
; template <int NT, int BM, int BN, bool PLAIN, int NSTAGE, bool EPI_LDS>
; __device__ __forceinline__ void gemm_tile(const Params& p, const GemmDesc& g, bf16_t* lds, const int tid) {
;     ...
;     __syncthreads();
;     constexpr int PPR = BN / 8;
;     constexpr int NIT = BM * PPR / NT;
;     bf16_t* o = (bf16_t*)g.out;
;     const long ldo = (g.epi == E_PROJ) ? LDP : (g.epi == E_RELU2 ? 8192 : 2048);
;     const int gcol = COL_BG + g.auxi * 2048;
; #pragma unroll 4
;     for (int i = 0; i < NIT; ++i) {
;       const int id = tid + NT * i;
;       const int row = id / PPR, pc = id % PPR;
;       u32x4 v = *(const u32x4*)(ct + row * CST + pc * 8);
;       bf16_t* op = o + (long)(m0e + row) * ldo + n0e + pc * 8;
;       if (g.epi == E_MERGE0 || g.epi == E_MERGEN) {
;         const u32x4 gt = *(const u32x4*)(((bf16_t*)(p.ws + OFF_proj)) + (long)(m0e + row) * LDP + gcol + n0e + pc * 8);
;         u32x4 pv = u32x4{0u, 0u, 0u, 0u};
;         if (g.epi == E_MERGEN) pv = *(const u32x4*)op;
; #pragma unroll
;         for (int e = 0; e < 4; ++e) {
;           const float g0 = sigmoid_f(__uint_as_float(gt[e] << 16)), g1 = sigmoid_f(__uint_as_float(gt[e] & 0xffff0000u));
;           const float a0 = __uint_as_float(v[e] << 16), a1 = __uint_as_float(v[e] & 0xffff0000u);
;           const float p0 = __uint_as_float(pv[e] << 16), p1 = __uint_as_float(pv[e] & 0xffff0000u);
;           v[e] = pack2(p0 + g0 * a0, p1 + g1 * a1);
;         }
;       }
;       *(u32x4*)op = v;
;     }
.LBB0_962:
	s_cmp_lg_u32 s56, 0
	s_cselect_b32 s58, s26, 0x2880
	s_ashr_i32 s25, s24, 31
	s_lshl_b64 s[26:27], s[24:25], 1
	s_add_u32 s26, s0, s26
	s_addc_u32 s27, s1, s27
	s_and_b32 s0, s56, 14
	s_cmp_lg_u32 s0, 6
	s_cselect_b64 s[28:29], -1, 0
	s_cmp_eq_u32 s56, 7
	s_cselect_b64 s[34:35], -1, 0
	s_lshl_b32 s0, s2, 1
	s_add_u32 s52, s84, s0
	v_cvt_pk_bf16_f32 v2, v6, v7
	v_cvt_pk_bf16_f32 v3, v8, v9
	s_mov_b32 s57, 0
	s_addc_u32 s53, s85, 0
	ds_write2_b64 v0, v[10:11], v[2:3] offset0:200 offset1:204
	s_waitcnt lgkmcnt(0)
	s_barrier
	s_andn2_b64 vcc, exec, s[28:29]
	s_cbranch_vccz .Lmy_plain
	s_and_b64 vcc, exec, s[34:35]
	s_cbranch_vccnz .Lmy_mergeN
.Lmy_merge0:
	v_lshrrev_b32_e32 v2, 5, v224
	v_and_b32_e32 v3, 31, v224
	v_lshlrev_b32_e32 v3, 4, v3
	v_mad_u32_u24 v18, v2, s50, v3
	v_add_u32_e32 v2, s23, v2
	v_mul_lo_u32 v160, v2, s48
	v_add_u32_e32 v160, v160, v3
	v_lshl_add_u32 v19, v2, 12, v3
	s_lshl_b32 s0, s24, 1
	s_add_u32 s60, s52, s0
	s_addc_u32 s61, s53, 0
	s_add_u32 s60, s60, 0x7cf6800
	s_addc_u32 s61, s61, 0
	s_mov_b64 s[62:63], s[26:27]
	s_mov_b64 s[64:65], s[26:27]
	v_mov_b32_e32 v16, 0
	v_mov_b32_e32 v17, 0
	global_load_dwordx4 v[186:189], v160, s[60:61]
	s_add_u32 s60, s60, 0x51000
	s_addc_u32 s61, s61, 0
	global_load_dwordx4 v[190:193], v160, s[60:61]
	s_add_u32 s60, s60, 0x51000
	s_addc_u32 s61, s61, 0
	global_load_dwordx4 v[194:197], v160, s[60:61]
	s_add_u32 s60, s60, 0x51000
	s_addc_u32 s61, s61, 0
	global_load_dwordx4 v[198:201], v160, s[60:61]
	s_add_u32 s60, s60, 0x51000
	s_addc_u32 s61, s61, 0
	s_mov_b32 s57, 0
.Lmy_merge0_loop:
	ds_read_b128 v[148:151], v18
	v_add_u32_e32 v18, 0x2200, v18
	s_waitcnt vmcnt(3)
	v_lshlrev_b32_e32 v2, 16, v186
	v_and_b32_e32 v3, 0xffff0000, v186
	v_mul_f32_e32 v2, 0xbfb8aa3b, v2
	v_mul_f32_e32 v3, 0xbfb8aa3b, v3
	v_exp_f32_e32 v2, v2
	v_exp_f32_e32 v3, v3
	s_nop 0
	v_pk_add_f32 v[2:3], v[2:3], 1.0 op_sel_hi:[1,0]
	s_nop 0
	v_div_scale_f32 v5, s[30:31], v3, v3, 1.0
	v_div_scale_f32 v4, s[30:31], v2, v2, 1.0
	v_rcp_f32_e32 v7, v5
	v_rcp_f32_e32 v6, v4
	v_fma_f32 v9, -v5, v7, 1.0
	v_fma_f32 v8, -v4, v6, 1.0
	v_fmac_f32_e32 v7, v9, v7
	v_fmac_f32_e32 v6, v8, v6
	v_div_scale_f32 v9, vcc, 1.0, v3, 1.0
	v_mul_f32_e32 v11, v9, v7
	v_fma_f32 v13, -v5, v11, v9
	v_fmac_f32_e32 v11, v13, v7
	v_fma_f32 v5, -v5, v11, v9
	v_div_fmas_f32 v5, v5, v7, v11
	v_div_fixup_f32 v3, v5, v3, 1.0
	v_div_scale_f32 v8, vcc, 1.0, v2, 1.0
	v_mul_f32_e32 v10, v8, v6
	v_fma_f32 v12, -v4, v10, v8
	v_fmac_f32_e32 v10, v12, v6
	v_fma_f32 v4, -v4, v10, v8
	v_div_fmas_f32 v4, v4, v6, v10
	v_div_fixup_f32 v2, v4, v2, 1.0
	s_waitcnt lgkmcnt(0)
	v_lshlrev_b32_e32 v14, 16, v148
	v_and_b32_e32 v15, 0xffff0000, v148
	v_pk_fma_f32 v[2:3], v[2:3], v[14:15], v[16:17]
	s_nop 0
	v_cvt_pk_bf16_f32 v156, v2, v3
	v_lshlrev_b32_e32 v2, 16, v187
	v_and_b32_e32 v3, 0xffff0000, v187
	v_mul_f32_e32 v2, 0xbfb8aa3b, v2
	v_mul_f32_e32 v3, 0xbfb8aa3b, v3
	v_exp_f32_e32 v2, v2
	v_exp_f32_e32 v3, v3
	s_nop 0
	v_pk_add_f32 v[2:3], v[2:3], 1.0 op_sel_hi:[1,0]
	s_nop 0
	v_div_scale_f32 v5, s[30:31], v3, v3, 1.0
	v_div_scale_f32 v4, s[30:31], v2, v2, 1.0
	v_rcp_f32_e32 v7, v5
	v_rcp_f32_e32 v6, v4
	v_fma_f32 v9, -v5, v7, 1.0
	v_fma_f32 v8, -v4, v6, 1.0
	v_fmac_f32_e32 v7, v9, v7
	v_fmac_f32_e32 v6, v8, v6
	v_div_scale_f32 v9, vcc, 1.0, v3, 1.0
	v_mul_f32_e32 v11, v9, v7
	v_fma_f32 v13, -v5, v11, v9
	v_fmac_f32_e32 v11, v13, v7
	v_fma_f32 v5, -v5, v11, v9
	v_div_fmas_f32 v5, v5, v7, v11
	v_div_fixup_f32 v3, v5, v3, 1.0
	v_div_scale_f32 v8, vcc, 1.0, v2, 1.0
	v_mul_f32_e32 v10, v8, v6
	v_fma_f32 v12, -v4, v10, v8
	v_fmac_f32_e32 v10, v12, v6
	v_fma_f32 v4, -v4, v10, v8
	v_div_fmas_f32 v4, v4, v6, v10
	v_div_fixup_f32 v2, v4, v2, 1.0
	v_lshlrev_b32_e32 v14, 16, v149
	v_and_b32_e32 v15, 0xffff0000, v149
	v_pk_fma_f32 v[2:3], v[2:3], v[14:15], v[16:17]
	s_nop 0
	v_cvt_pk_bf16_f32 v157, v2, v3
	v_lshlrev_b32_e32 v2, 16, v188
	v_and_b32_e32 v3, 0xffff0000, v188
	v_mul_f32_e32 v2, 0xbfb8aa3b, v2
	v_mul_f32_e32 v3, 0xbfb8aa3b, v3
	v_exp_f32_e32 v2, v2
	v_exp_f32_e32 v3, v3
	s_nop 0
	v_pk_add_f32 v[2:3], v[2:3], 1.0 op_sel_hi:[1,0]
	s_nop 0
	v_div_scale_f32 v5, s[30:31], v3, v3, 1.0
	v_div_scale_f32 v4, s[30:31], v2, v2, 1.0
	v_rcp_f32_e32 v7, v5
	v_rcp_f32_e32 v6, v4
	v_fma_f32 v9, -v5, v7, 1.0
	v_fma_f32 v8, -v4, v6, 1.0
	v_fmac_f32_e32 v7, v9, v7
	v_fmac_f32_e32 v6, v8, v6
	v_div_scale_f32 v9, vcc, 1.0, v3, 1.0
	v_mul_f32_e32 v11, v9, v7
	v_fma_f32 v13, -v5, v11, v9
	v_fmac_f32_e32 v11, v13, v7
	v_fma_f32 v5, -v5, v11, v9
	v_div_fmas_f32 v5, v5, v7, v11
	v_div_fixup_f32 v3, v5, v3, 1.0
	v_div_scale_f32 v8, vcc, 1.0, v2, 1.0
	v_mul_f32_e32 v10, v8, v6
	v_fma_f32 v12, -v4, v10, v8
	v_fmac_f32_e32 v10, v12, v6
	v_fma_f32 v4, -v4, v10, v8
	v_div_fmas_f32 v4, v4, v6, v10
	v_div_fixup_f32 v2, v4, v2, 1.0
	v_lshlrev_b32_e32 v14, 16, v150
	v_and_b32_e32 v15, 0xffff0000, v150
	v_pk_fma_f32 v[2:3], v[2:3], v[14:15], v[16:17]
	s_nop 0
	v_cvt_pk_bf16_f32 v158, v2, v3
	v_lshlrev_b32_e32 v2, 16, v189
	v_and_b32_e32 v3, 0xffff0000, v189
	v_mul_f32_e32 v2, 0xbfb8aa3b, v2
	v_mul_f32_e32 v3, 0xbfb8aa3b, v3
	v_exp_f32_e32 v2, v2
	v_exp_f32_e32 v3, v3
	s_nop 0
	v_pk_add_f32 v[2:3], v[2:3], 1.0 op_sel_hi:[1,0]
	s_nop 0
	v_div_scale_f32 v5, s[30:31], v3, v3, 1.0
	v_div_scale_f32 v4, s[30:31], v2, v2, 1.0
	v_rcp_f32_e32 v7, v5
	v_rcp_f32_e32 v6, v4
	v_fma_f32 v9, -v5, v7, 1.0
	v_fma_f32 v8, -v4, v6, 1.0
	v_fmac_f32_e32 v7, v9, v7
	v_fmac_f32_e32 v6, v8, v6
	v_div_scale_f32 v9, vcc, 1.0, v3, 1.0
	v_mul_f32_e32 v11, v9, v7
	v_fma_f32 v13, -v5, v11, v9
	v_fmac_f32_e32 v11, v13, v7
	v_fma_f32 v5, -v5, v11, v9
	v_div_fmas_f32 v5, v5, v7, v11
	v_div_fixup_f32 v3, v5, v3, 1.0
	v_div_scale_f32 v8, vcc, 1.0, v2, 1.0
	v_mul_f32_e32 v10, v8, v6
	v_fma_f32 v12, -v4, v10, v8
	v_fmac_f32_e32 v10, v12, v6
	v_fma_f32 v4, -v4, v10, v8
	v_div_fmas_f32 v4, v4, v6, v10
	v_div_fixup_f32 v2, v4, v2, 1.0
	v_lshlrev_b32_e32 v14, 16, v151
	v_and_b32_e32 v15, 0xffff0000, v151
	v_pk_fma_f32 v[2:3], v[2:3], v[14:15], v[16:17]
	s_nop 0
	v_cvt_pk_bf16_f32 v159, v2, v3
	global_load_dwordx4 v[186:189], v160, s[60:61]
	s_add_u32 s60, s60, 0x51000
	s_addc_u32 s61, s61, 0
	global_store_dwordx4 v19, v[156:159], s[64:65]
	s_add_u32 s64, s64, 0x10000
	s_addc_u32 s65, s65, 0
	ds_read_b128 v[148:151], v18
	v_add_u32_e32 v18, 0x2200, v18
	s_waitcnt vmcnt(4)
; __device__ __forceinline__ float sigmoid_f(float x) { return 1.f / (1.f + __expf(-x)); }
; template <int NT, int BM, int BN, bool PLAIN, int NSTAGE, bool EPI_LDS>
; __device__ __forceinline__ void gemm_tile(const Params& p, const GemmDesc& g, bf16_t* lds, const int tid) {
;     ...
;     for (int i = 0; i < NIT; ++i) {
;       const int id = tid + NT * i;
;       const int row = id / PPR, pc = id % PPR;
;       u32x4 v = *(const u32x4*)(ct + row * CST + pc * 8);
;       bf16_t* op = o + (long)(m0e + row) * ldo + n0e + pc * 8;
;       if (g.epi == E_MERGE0 || g.epi == E_MERGEN) {
;         const u32x4 gt = *(const u32x4*)(((bf16_t*)(p.ws + OFF_proj)) + (long)(m0e + row) * LDP + gcol + n0e + pc * 8);
;         u32x4 pv = u32x4{0u, 0u, 0u, 0u};
;         if (g.epi == E_MERGEN) pv = *(const u32x4*)op;
; #pragma unroll
;         for (int e = 0; e < 4; ++e) {
;           const float g0 = sigmoid_f(__uint_as_float(gt[e] << 16)), g1 = sigmoid_f(__uint_as_float(gt[e] & 0xffff0000u));
;           const float a0 = __uint_as_float(v[e] << 16), a1 = __uint_as_float(v[e] & 0xffff0000u);
;           const float p0 = __uint_as_float(pv[e] << 16), p1 = __uint_as_float(pv[e] & 0xffff0000u);
;           v[e] = pack2(p0 + g0 * a0, p1 + g1 * a1);
;         }
;       }
;       *(u32x4*)op = v;
;     }
	v_lshlrev_b32_e32 v2, 16, v190
	v_and_b32_e32 v3, 0xffff0000, v190
	v_mul_f32_e32 v2, 0xbfb8aa3b, v2
	v_mul_f32_e32 v3, 0xbfb8aa3b, v3
	v_exp_f32_e32 v2, v2
	v_exp_f32_e32 v3, v3
	s_nop 0
	v_pk_add_f32 v[2:3], v[2:3], 1.0 op_sel_hi:[1,0]
	s_nop 0
	v_div_scale_f32 v5, s[30:31], v3, v3, 1.0
	v_div_scale_f32 v4, s[30:31], v2, v2, 1.0
	v_rcp_f32_e32 v7, v5
	v_rcp_f32_e32 v6, v4
	v_fma_f32 v9, -v5, v7, 1.0
	v_fma_f32 v8, -v4, v6, 1.0
	v_fmac_f32_e32 v7, v9, v7
	v_fmac_f32_e32 v6, v8, v6
	v_div_scale_f32 v9, vcc, 1.0, v3, 1.0
	v_mul_f32_e32 v11, v9, v7
	v_fma_f32 v13, -v5, v11, v9
	v_fmac_f32_e32 v11, v13, v7
	v_fma_f32 v5, -v5, v11, v9
	v_div_fmas_f32 v5, v5, v7, v11
	v_div_fixup_f32 v3, v5, v3, 1.0
	v_div_scale_f32 v8, vcc, 1.0, v2, 1.0
	v_mul_f32_e32 v10, v8, v6
	v_fma_f32 v12, -v4, v10, v8
	v_fmac_f32_e32 v10, v12, v6
	v_fma_f32 v4, -v4, v10, v8
	v_div_fmas_f32 v4, v4, v6, v10
	v_div_fixup_f32 v2, v4, v2, 1.0
	s_waitcnt lgkmcnt(0)
	v_lshlrev_b32_e32 v14, 16, v148
	v_and_b32_e32 v15, 0xffff0000, v148
	v_pk_fma_f32 v[2:3], v[2:3], v[14:15], v[16:17]
	s_nop 0
	v_cvt_pk_bf16_f32 v156, v2, v3
	v_lshlrev_b32_e32 v2, 16, v191
	v_and_b32_e32 v3, 0xffff0000, v191
	v_mul_f32_e32 v2, 0xbfb8aa3b, v2
	v_mul_f32_e32 v3, 0xbfb8aa3b, v3
	v_exp_f32_e32 v2, v2
	v_exp_f32_e32 v3, v3
	s_nop 0
	v_pk_add_f32 v[2:3], v[2:3], 1.0 op_sel_hi:[1,0]
	s_nop 0
	v_div_scale_f32 v5, s[30:31], v3, v3, 1.0
	v_div_scale_f32 v4, s[30:31], v2, v2, 1.0
	v_rcp_f32_e32 v7, v5
	v_rcp_f32_e32 v6, v4
	v_fma_f32 v9, -v5, v7, 1.0
	v_fma_f32 v8, -v4, v6, 1.0
	v_fmac_f32_e32 v7, v9, v7
	v_fmac_f32_e32 v6, v8, v6
	v_div_scale_f32 v9, vcc, 1.0, v3, 1.0
	v_mul_f32_e32 v11, v9, v7
	v_fma_f32 v13, -v5, v11, v9
	v_fmac_f32_e32 v11, v13, v7
	v_fma_f32 v5, -v5, v11, v9
	v_div_fmas_f32 v5, v5, v7, v11
	v_div_fixup_f32 v3, v5, v3, 1.0
	v_div_scale_f32 v8, vcc, 1.0, v2, 1.0
	v_mul_f32_e32 v10, v8, v6
	v_fma_f32 v12, -v4, v10, v8
	v_fmac_f32_e32 v10, v12, v6
	v_fma_f32 v4, -v4, v10, v8
	v_div_fmas_f32 v4, v4, v6, v10
	v_div_fixup_f32 v2, v4, v2, 1.0
	v_lshlrev_b32_e32 v14, 16, v149
	v_and_b32_e32 v15, 0xffff0000, v149
	v_pk_fma_f32 v[2:3], v[2:3], v[14:15], v[16:17]
	s_nop 0
	v_cvt_pk_bf16_f32 v157, v2, v3
	v_lshlrev_b32_e32 v2, 16, v192
	v_and_b32_e32 v3, 0xffff0000, v192
	v_mul_f32_e32 v2, 0xbfb8aa3b, v2
	v_mul_f32_e32 v3, 0xbfb8aa3b, v3
	v_exp_f32_e32 v2, v2
	v_exp_f32_e32 v3, v3
	s_nop 0
	v_pk_add_f32 v[2:3], v[2:3], 1.0 op_sel_hi:[1,0]
	s_nop 0
	v_div_scale_f32 v5, s[30:31], v3, v3, 1.0
	v_div_scale_f32 v4, s[30:31], v2, v2, 1.0
	v_rcp_f32_e32 v7, v5
	v_rcp_f32_e32 v6, v4
	v_fma_f32 v9, -v5, v7, 1.0
	v_fma_f32 v8, -v4, v6, 1.0
	v_fmac_f32_e32 v7, v9, v7
	v_fmac_f32_e32 v6, v8, v6
	v_div_scale_f32 v9, vcc, 1.0, v3, 1.0
	v_mul_f32_e32 v11, v9, v7
	v_fma_f32 v13, -v5, v11, v9
	v_fmac_f32_e32 v11, v13, v7
	v_fma_f32 v5, -v5, v11, v9
	v_div_fmas_f32 v5, v5, v7, v11
	v_div_fixup_f32 v3, v5, v3, 1.0
	v_div_scale_f32 v8, vcc, 1.0, v2, 1.0
	v_mul_f32_e32 v10, v8, v6
	v_fma_f32 v12, -v4, v10, v8
	v_fmac_f32_e32 v10, v12, v6
	v_fma_f32 v4, -v4, v10, v8
	v_div_fmas_f32 v4, v4, v6, v10
	v_div_fixup_f32 v2, v4, v2, 1.0
	v_lshlrev_b32_e32 v14, 16, v150
	v_and_b32_e32 v15, 0xffff0000, v150
	v_pk_fma_f32 v[2:3], v[2:3], v[14:15], v[16:17]
	s_nop 0
	v_cvt_pk_bf16_f32 v158, v2, v3
	v_lshlrev_b32_e32 v2, 16, v193
	v_and_b32_e32 v3, 0xffff0000, v193
	v_mul_f32_e32 v2, 0xbfb8aa3b, v2
	v_mul_f32_e32 v3, 0xbfb8aa3b, v3
	v_exp_f32_e32 v2, v2
	v_exp_f32_e32 v3, v3
	s_nop 0
	v_pk_add_f32 v[2:3], v[2:3], 1.0 op_sel_hi:[1,0]
	s_nop 0
	v_div_scale_f32 v5, s[30:31], v3, v3, 1.0
	v_div_scale_f32 v4, s[30:31], v2, v2, 1.0
	v_rcp_f32_e32 v7, v5
	v_rcp_f32_e32 v6, v4
	v_fma_f32 v9, -v5, v7, 1.0
	v_fma_f32 v8, -v4, v6, 1.0
	v_fmac_f32_e32 v7, v9, v7
	v_fmac_f32_e32 v6, v8, v6
	v_div_scale_f32 v9, vcc, 1.0, v3, 1.0
	v_mul_f32_e32 v11, v9, v7
	v_fma_f32 v13, -v5, v11, v9
	v_fmac_f32_e32 v11, v13, v7
	v_fma_f32 v5, -v5, v11, v9
	v_div_fmas_f32 v5, v5, v7, v11
	v_div_fixup_f32 v3, v5, v3, 1.0
	v_div_scale_f32 v8, vcc, 1.0, v2, 1.0
	v_mul_f32_e32 v10, v8, v6
	v_fma_f32 v12, -v4, v10, v8
	v_fmac_f32_e32 v10, v12, v6
	v_fma_f32 v4, -v4, v10, v8
	v_div_fmas_f32 v4, v4, v6, v10
	v_div_fixup_f32 v2, v4, v2, 1.0
	v_lshlrev_b32_e32 v14, 16, v151
	v_and_b32_e32 v15, 0xffff0000, v151
	v_pk_fma_f32 v[2:3], v[2:3], v[14:15], v[16:17]
	s_nop 0
	v_cvt_pk_bf16_f32 v159, v2, v3
	global_load_dwordx4 v[190:193], v160, s[60:61]
	s_add_u32 s60, s60, 0x51000
	s_addc_u32 s61, s61, 0
	global_store_dwordx4 v19, v[156:159], s[64:65]
	s_add_u32 s64, s64, 0x10000
	s_addc_u32 s65, s65, 0
	ds_read_b128 v[148:151], v18
	v_add_u32_e32 v18, 0x2200, v18
	s_waitcnt vmcnt(5)
	v_lshlrev_b32_e32 v2, 16, v194
	v_and_b32_e32 v3, 0xffff0000, v194
	v_mul_f32_e32 v2, 0xbfb8aa3b, v2
	v_mul_f32_e32 v3, 0xbfb8aa3b, v3
	v_exp_f32_e32 v2, v2
	v_exp_f32_e32 v3, v3
	s_nop 0
	v_pk_add_f32 v[2:3], v[2:3], 1.0 op_sel_hi:[1,0]
	s_nop 0
	v_div_scale_f32 v5, s[30:31], v3, v3, 1.0
	v_div_scale_f32 v4, s[30:31], v2, v2, 1.0
	v_rcp_f32_e32 v7, v5
	v_rcp_f32_e32 v6, v4
	v_fma_f32 v9, -v5, v7, 1.0
	v_fma_f32 v8, -v4, v6, 1.0
	v_fmac_f32_e32 v7, v9, v7
	v_fmac_f32_e32 v6, v8, v6
	v_div_scale_f32 v9, vcc, 1.0, v3, 1.0
	v_mul_f32_e32 v11, v9, v7
	v_fma_f32 v13, -v5, v11, v9
	v_fmac_f32_e32 v11, v13, v7
	v_fma_f32 v5, -v5, v11, v9
	v_div_fmas_f32 v5, v5, v7, v11
	v_div_fixup_f32 v3, v5, v3, 1.0
	v_div_scale_f32 v8, vcc, 1.0, v2, 1.0
	v_mul_f32_e32 v10, v8, v6
	v_fma_f32 v12, -v4, v10, v8
	v_fmac_f32_e32 v10, v12, v6
	v_fma_f32 v4, -v4, v10, v8
	v_div_fmas_f32 v4, v4, v6, v10
	v_div_fixup_f32 v2, v4, v2, 1.0
	s_waitcnt lgkmcnt(0)
; __device__ __forceinline__ float sigmoid_f(float x) { return 1.f / (1.f + __expf(-x)); }
; template <int NT, int BM, int BN, bool PLAIN, int NSTAGE, bool EPI_LDS>
; __device__ __forceinline__ void gemm_tile(const Params& p, const GemmDesc& g, bf16_t* lds, const int tid) {
;     ...
;     for (int i = 0; i < NIT; ++i) {
;       const int id = tid + NT * i;
;       const int row = id / PPR, pc = id % PPR;
;       u32x4 v = *(const u32x4*)(ct + row * CST + pc * 8);
;       bf16_t* op = o + (long)(m0e + row) * ldo + n0e + pc * 8;
;       if (g.epi == E_MERGE0 || g.epi == E_MERGEN) {
;         const u32x4 gt = *(const u32x4*)(((bf16_t*)(p.ws + OFF_proj)) + (long)(m0e + row) * LDP + gcol + n0e + pc * 8);
;         u32x4 pv = u32x4{0u, 0u, 0u, 0u};
;         if (g.epi == E_MERGEN) pv = *(const u32x4*)op;
; #pragma unroll
;         for (int e = 0; e < 4; ++e) {
;           const float g0 = sigmoid_f(__uint_as_float(gt[e] << 16)), g1 = sigmoid_f(__uint_as_float(gt[e] & 0xffff0000u));
;           const float a0 = __uint_as_float(v[e] << 16), a1 = __uint_as_float(v[e] & 0xffff0000u);
;           const float p0 = __uint_as_float(pv[e] << 16), p1 = __uint_as_float(pv[e] & 0xffff0000u);
;           v[e] = pack2(p0 + g0 * a0, p1 + g1 * a1);
;         }
;       }
;       *(u32x4*)op = v;
;     }
	v_lshlrev_b32_e32 v14, 16, v148
	v_and_b32_e32 v15, 0xffff0000, v148
	v_pk_fma_f32 v[2:3], v[2:3], v[14:15], v[16:17]
	s_nop 0
	v_cvt_pk_bf16_f32 v156, v2, v3
	v_lshlrev_b32_e32 v2, 16, v195
	v_and_b32_e32 v3, 0xffff0000, v195
	v_mul_f32_e32 v2, 0xbfb8aa3b, v2
	v_mul_f32_e32 v3, 0xbfb8aa3b, v3
	v_exp_f32_e32 v2, v2
	v_exp_f32_e32 v3, v3
	s_nop 0
	v_pk_add_f32 v[2:3], v[2:3], 1.0 op_sel_hi:[1,0]
	s_nop 0
	v_div_scale_f32 v5, s[30:31], v3, v3, 1.0
	v_div_scale_f32 v4, s[30:31], v2, v2, 1.0
	v_rcp_f32_e32 v7, v5
	v_rcp_f32_e32 v6, v4
	v_fma_f32 v9, -v5, v7, 1.0
	v_fma_f32 v8, -v4, v6, 1.0
	v_fmac_f32_e32 v7, v9, v7
	v_fmac_f32_e32 v6, v8, v6
	v_div_scale_f32 v9, vcc, 1.0, v3, 1.0
	v_mul_f32_e32 v11, v9, v7
	v_fma_f32 v13, -v5, v11, v9
	v_fmac_f32_e32 v11, v13, v7
	v_fma_f32 v5, -v5, v11, v9
	v_div_fmas_f32 v5, v5, v7, v11
	v_div_fixup_f32 v3, v5, v3, 1.0
	v_div_scale_f32 v8, vcc, 1.0, v2, 1.0
	v_mul_f32_e32 v10, v8, v6
	v_fma_f32 v12, -v4, v10, v8
	v_fmac_f32_e32 v10, v12, v6
	v_fma_f32 v4, -v4, v10, v8
	v_div_fmas_f32 v4, v4, v6, v10
	v_div_fixup_f32 v2, v4, v2, 1.0
	v_lshlrev_b32_e32 v14, 16, v149
	v_and_b32_e32 v15, 0xffff0000, v149
	v_pk_fma_f32 v[2:3], v[2:3], v[14:15], v[16:17]
	s_nop 0
	v_cvt_pk_bf16_f32 v157, v2, v3
	v_lshlrev_b32_e32 v2, 16, v196
	v_and_b32_e32 v3, 0xffff0000, v196
	v_mul_f32_e32 v2, 0xbfb8aa3b, v2
	v_mul_f32_e32 v3, 0xbfb8aa3b, v3
	v_exp_f32_e32 v2, v2
	v_exp_f32_e32 v3, v3
	s_nop 0
	v_pk_add_f32 v[2:3], v[2:3], 1.0 op_sel_hi:[1,0]
	s_nop 0
	v_div_scale_f32 v5, s[30:31], v3, v3, 1.0
	v_div_scale_f32 v4, s[30:31], v2, v2, 1.0
	v_rcp_f32_e32 v7, v5
	v_rcp_f32_e32 v6, v4
	v_fma_f32 v9, -v5, v7, 1.0
	v_fma_f32 v8, -v4, v6, 1.0
	v_fmac_f32_e32 v7, v9, v7
	v_fmac_f32_e32 v6, v8, v6
	v_div_scale_f32 v9, vcc, 1.0, v3, 1.0
	v_mul_f32_e32 v11, v9, v7
	v_fma_f32 v13, -v5, v11, v9
	v_fmac_f32_e32 v11, v13, v7
	v_fma_f32 v5, -v5, v11, v9
	v_div_fmas_f32 v5, v5, v7, v11
	v_div_fixup_f32 v3, v5, v3, 1.0
	v_div_scale_f32 v8, vcc, 1.0, v2, 1.0
	v_mul_f32_e32 v10, v8, v6
	v_fma_f32 v12, -v4, v10, v8
	v_fmac_f32_e32 v10, v12, v6
	v_fma_f32 v4, -v4, v10, v8
	v_div_fmas_f32 v4, v4, v6, v10
	v_div_fixup_f32 v2, v4, v2, 1.0
	v_lshlrev_b32_e32 v14, 16, v150
	v_and_b32_e32 v15, 0xffff0000, v150
	v_pk_fma_f32 v[2:3], v[2:3], v[14:15], v[16:17]
	s_nop 0
	v_cvt_pk_bf16_f32 v158, v2, v3
	v_lshlrev_b32_e32 v2, 16, v197
	v_and_b32_e32 v3, 0xffff0000, v197
	v_mul_f32_e32 v2, 0xbfb8aa3b, v2
	v_mul_f32_e32 v3, 0xbfb8aa3b, v3
	v_exp_f32_e32 v2, v2
	v_exp_f32_e32 v3, v3
	s_nop 0
	v_pk_add_f32 v[2:3], v[2:3], 1.0 op_sel_hi:[1,0]
	s_nop 0
	v_div_scale_f32 v5, s[30:31], v3, v3, 1.0
	v_div_scale_f32 v4, s[30:31], v2, v2, 1.0
	v_rcp_f32_e32 v7, v5
	v_rcp_f32_e32 v6, v4
	v_fma_f32 v9, -v5, v7, 1.0
	v_fma_f32 v8, -v4, v6, 1.0
	v_fmac_f32_e32 v7, v9, v7
	v_fmac_f32_e32 v6, v8, v6
	v_div_scale_f32 v9, vcc, 1.0, v3, 1.0
	v_mul_f32_e32 v11, v9, v7
	v_fma_f32 v13, -v5, v11, v9
	v_fmac_f32_e32 v11, v13, v7
	v_fma_f32 v5, -v5, v11, v9
	v_div_fmas_f32 v5, v5, v7, v11
	v_div_fixup_f32 v3, v5, v3, 1.0
	v_div_scale_f32 v8, vcc, 1.0, v2, 1.0
	v_mul_f32_e32 v10, v8, v6
	v_fma_f32 v12, -v4, v10, v8
	v_fmac_f32_e32 v10, v12, v6
	v_fma_f32 v4, -v4, v10, v8
	v_div_fmas_f32 v4, v4, v6, v10
	v_div_fixup_f32 v2, v4, v2, 1.0
	v_lshlrev_b32_e32 v14, 16, v151
	v_and_b32_e32 v15, 0xffff0000, v151
	v_pk_fma_f32 v[2:3], v[2:3], v[14:15], v[16:17]
	s_nop 0
	v_cvt_pk_bf16_f32 v159, v2, v3
	global_load_dwordx4 v[194:197], v160, s[60:61]
	s_add_u32 s60, s60, 0x51000
	s_addc_u32 s61, s61, 0
	global_store_dwordx4 v19, v[156:159], s[64:65]
	s_add_u32 s64, s64, 0x10000
	s_addc_u32 s65, s65, 0
	ds_read_b128 v[148:151], v18
	v_add_u32_e32 v18, 0x2200, v18
	s_waitcnt vmcnt(6)
	v_lshlrev_b32_e32 v2, 16, v198
	v_and_b32_e32 v3, 0xffff0000, v198
	v_mul_f32_e32 v2, 0xbfb8aa3b, v2
	v_mul_f32_e32 v3, 0xbfb8aa3b, v3
	v_exp_f32_e32 v2, v2
	v_exp_f32_e32 v3, v3
	s_nop 0
	v_pk_add_f32 v[2:3], v[2:3], 1.0 op_sel_hi:[1,0]
	s_nop 0
	v_div_scale_f32 v5, s[30:31], v3, v3, 1.0
	v_div_scale_f32 v4, s[30:31], v2, v2, 1.0
	v_rcp_f32_e32 v7, v5
	v_rcp_f32_e32 v6, v4
	v_fma_f32 v9, -v5, v7, 1.0
	v_fma_f32 v8, -v4, v6, 1.0
	v_fmac_f32_e32 v7, v9, v7
	v_fmac_f32_e32 v6, v8, v6
	v_div_scale_f32 v9, vcc, 1.0, v3, 1.0
	v_mul_f32_e32 v11, v9, v7
	v_fma_f32 v13, -v5, v11, v9
	v_fmac_f32_e32 v11, v13, v7
	v_fma_f32 v5, -v5, v11, v9
	v_div_fmas_f32 v5, v5, v7, v11
	v_div_fixup_f32 v3, v5, v3, 1.0
	v_div_scale_f32 v8, vcc, 1.0, v2, 1.0
	v_mul_f32_e32 v10, v8, v6
	v_fma_f32 v12, -v4, v10, v8
	v_fmac_f32_e32 v10, v12, v6
	v_fma_f32 v4, -v4, v10, v8
	v_div_fmas_f32 v4, v4, v6, v10
	v_div_fixup_f32 v2, v4, v2, 1.0
	s_waitcnt lgkmcnt(0)
; __device__ __forceinline__ float sigmoid_f(float x) { return 1.f / (1.f + __expf(-x)); }
; template <int NT, int BM, int BN, bool PLAIN, int NSTAGE, bool EPI_LDS>
; __device__ __forceinline__ void gemm_tile(const Params& p, const GemmDesc& g, bf16_t* lds, const int tid) {
;     ...
;     for (int i = 0; i < NIT; ++i) {
;       const int id = tid + NT * i;
;       const int row = id / PPR, pc = id % PPR;
;       u32x4 v = *(const u32x4*)(ct + row * CST + pc * 8);
;       bf16_t* op = o + (long)(m0e + row) * ldo + n0e + pc * 8;
;       if (g.epi == E_MERGE0 || g.epi == E_MERGEN) {
;         const u32x4 gt = *(const u32x4*)(((bf16_t*)(p.ws + OFF_proj)) + (long)(m0e + row) * LDP + gcol + n0e + pc * 8);
;         u32x4 pv = u32x4{0u, 0u, 0u, 0u};
;         if (g.epi == E_MERGEN) pv = *(const u32x4*)op;
; #pragma unroll
;         for (int e = 0; e < 4; ++e) {
;           const float g0 = sigmoid_f(__uint_as_float(gt[e] << 16)), g1 = sigmoid_f(__uint_as_float(gt[e] & 0xffff0000u));
;           const float a0 = __uint_as_float(v[e] << 16), a1 = __uint_as_float(v[e] & 0xffff0000u);
;           const float p0 = __uint_as_float(pv[e] << 16), p1 = __uint_as_float(pv[e] & 0xffff0000u);
;           v[e] = pack2(p0 + g0 * a0, p1 + g1 * a1);
;         }
;       }
;       *(u32x4*)op = v;
;     }
	v_lshlrev_b32_e32 v14, 16, v148
	v_and_b32_e32 v15, 0xffff0000, v148
	v_pk_fma_f32 v[2:3], v[2:3], v[14:15], v[16:17]
	s_nop 0
	v_cvt_pk_bf16_f32 v156, v2, v3
	v_lshlrev_b32_e32 v2, 16, v199
	v_and_b32_e32 v3, 0xffff0000, v199
	v_mul_f32_e32 v2, 0xbfb8aa3b, v2
	v_mul_f32_e32 v3, 0xbfb8aa3b, v3
	v_exp_f32_e32 v2, v2
	v_exp_f32_e32 v3, v3
	s_nop 0
	v_pk_add_f32 v[2:3], v[2:3], 1.0 op_sel_hi:[1,0]
	s_nop 0
	v_div_scale_f32 v5, s[30:31], v3, v3, 1.0
	v_div_scale_f32 v4, s[30:31], v2, v2, 1.0
	v_rcp_f32_e32 v7, v5
	v_rcp_f32_e32 v6, v4
	v_fma_f32 v9, -v5, v7, 1.0
	v_fma_f32 v8, -v4, v6, 1.0
	v_fmac_f32_e32 v7, v9, v7
	v_fmac_f32_e32 v6, v8, v6
	v_div_scale_f32 v9, vcc, 1.0, v3, 1.0
	v_mul_f32_e32 v11, v9, v7
	v_fma_f32 v13, -v5, v11, v9
	v_fmac_f32_e32 v11, v13, v7
	v_fma_f32 v5, -v5, v11, v9
	v_div_fmas_f32 v5, v5, v7, v11
	v_div_fixup_f32 v3, v5, v3, 1.0
	v_div_scale_f32 v8, vcc, 1.0, v2, 1.0
	v_mul_f32_e32 v10, v8, v6
	v_fma_f32 v12, -v4, v10, v8
	v_fmac_f32_e32 v10, v12, v6
	v_fma_f32 v4, -v4, v10, v8
	v_div_fmas_f32 v4, v4, v6, v10
	v_div_fixup_f32 v2, v4, v2, 1.0
	v_lshlrev_b32_e32 v14, 16, v149
	v_and_b32_e32 v15, 0xffff0000, v149
	v_pk_fma_f32 v[2:3], v[2:3], v[14:15], v[16:17]
	s_nop 0
	v_cvt_pk_bf16_f32 v157, v2, v3
	v_lshlrev_b32_e32 v2, 16, v200
	v_and_b32_e32 v3, 0xffff0000, v200
	v_mul_f32_e32 v2, 0xbfb8aa3b, v2
	v_mul_f32_e32 v3, 0xbfb8aa3b, v3
	v_exp_f32_e32 v2, v2
	v_exp_f32_e32 v3, v3
	s_nop 0
	v_pk_add_f32 v[2:3], v[2:3], 1.0 op_sel_hi:[1,0]
	s_nop 0
	v_div_scale_f32 v5, s[30:31], v3, v3, 1.0
	v_div_scale_f32 v4, s[30:31], v2, v2, 1.0
	v_rcp_f32_e32 v7, v5
	v_rcp_f32_e32 v6, v4
	v_fma_f32 v9, -v5, v7, 1.0
	v_fma_f32 v8, -v4, v6, 1.0
	v_fmac_f32_e32 v7, v9, v7
	v_fmac_f32_e32 v6, v8, v6
	v_div_scale_f32 v9, vcc, 1.0, v3, 1.0
	v_mul_f32_e32 v11, v9, v7
	v_fma_f32 v13, -v5, v11, v9
	v_fmac_f32_e32 v11, v13, v7
	v_fma_f32 v5, -v5, v11, v9
	v_div_fmas_f32 v5, v5, v7, v11
	v_div_fixup_f32 v3, v5, v3, 1.0
	v_div_scale_f32 v8, vcc, 1.0, v2, 1.0
	v_mul_f32_e32 v10, v8, v6
	v_fma_f32 v12, -v4, v10, v8
	v_fmac_f32_e32 v10, v12, v6
	v_fma_f32 v4, -v4, v10, v8
	v_div_fmas_f32 v4, v4, v6, v10
	v_div_fixup_f32 v2, v4, v2, 1.0
	v_lshlrev_b32_e32 v14, 16, v150
	v_and_b32_e32 v15, 0xffff0000, v150
	v_pk_fma_f32 v[2:3], v[2:3], v[14:15], v[16:17]
	s_nop 0
	v_cvt_pk_bf16_f32 v158, v2, v3
	v_lshlrev_b32_e32 v2, 16, v201
	v_and_b32_e32 v3, 0xffff0000, v201
	v_mul_f32_e32 v2, 0xbfb8aa3b, v2
	v_mul_f32_e32 v3, 0xbfb8aa3b, v3
	v_exp_f32_e32 v2, v2
	v_exp_f32_e32 v3, v3
	s_nop 0
	v_pk_add_f32 v[2:3], v[2:3], 1.0 op_sel_hi:[1,0]
	s_nop 0
	v_div_scale_f32 v5, s[30:31], v3, v3, 1.0
	v_div_scale_f32 v4, s[30:31], v2, v2, 1.0
	v_rcp_f32_e32 v7, v5
	v_rcp_f32_e32 v6, v4
	v_fma_f32 v9, -v5, v7, 1.0
	v_fma_f32 v8, -v4, v6, 1.0
	v_fmac_f32_e32 v7, v9, v7
	v_fmac_f32_e32 v6, v8, v6
	v_div_scale_f32 v9, vcc, 1.0, v3, 1.0
	v_mul_f32_e32 v11, v9, v7
	v_fma_f32 v13, -v5, v11, v9
	v_fmac_f32_e32 v11, v13, v7
	v_fma_f32 v5, -v5, v11, v9
	v_div_fmas_f32 v5, v5, v7, v11
	v_div_fixup_f32 v3, v5, v3, 1.0
	v_div_scale_f32 v8, vcc, 1.0, v2, 1.0
	v_mul_f32_e32 v10, v8, v6
	v_fma_f32 v12, -v4, v10, v8
	v_fmac_f32_e32 v10, v12, v6
	v_fma_f32 v4, -v4, v10, v8
	v_div_fmas_f32 v4, v4, v6, v10
	v_div_fixup_f32 v2, v4, v2, 1.0
	v_lshlrev_b32_e32 v14, 16, v151
	v_and_b32_e32 v15, 0xffff0000, v151
	v_pk_fma_f32 v[2:3], v[2:3], v[14:15], v[16:17]
	s_nop 0
	v_cvt_pk_bf16_f32 v159, v2, v3
	global_load_dwordx4 v[198:201], v160, s[60:61]
	s_add_u32 s60, s60, 0x51000
	s_addc_u32 s61, s61, 0
	global_store_dwordx4 v19, v[156:159], s[64:65]
	s_add_u32 s64, s64, 0x10000
	s_addc_u32 s65, s65, 0
	s_add_i32 s57, s57, 1
	s_cmp_eq_u32 s57, 3
	s_cselect_b32 s0, 0x510000, 0
	s_cselect_b32 s2, 0x100000, 0
	s_sub_u32 s60, s60, s0
	s_subb_u32 s61, s61, 0
	s_cmp_lt_u32 s57, 4
	s_cbranch_scc1 .Lmy_merge0_loop
	s_branch .LBB0_888
.Lmy_mergeN:
	v_lshrrev_b32_e32 v2, 5, v224
	v_and_b32_e32 v3, 31, v224
	v_lshlrev_b32_e32 v3, 4, v3
	v_mad_u32_u24 v18, v2, s50, v3
	v_add_u32_e32 v2, s23, v2
	v_mul_lo_u32 v160, v2, s48
	v_add_u32_e32 v160, v160, v3
	v_lshl_add_u32 v19, v2, 12, v3
	s_lshl_b32 s0, s24, 1
	s_add_u32 s60, s52, s0
	s_addc_u32 s61, s53, 0
	s_add_u32 s60, s60, 0x7cf6800
	s_addc_u32 s61, s61, 0
	s_mov_b64 s[62:63], s[26:27]
	s_mov_b64 s[64:65], s[26:27]
	global_load_dwordx4 v[186:189], v160, s[60:61]
	global_load_dwordx4 v[226:229], v19, s[62:63]
	s_add_u32 s60, s60, 0x51000
	s_addc_u32 s61, s61, 0
	s_add_u32 s62, s62, 0x10000
	s_addc_u32 s63, s63, 0
	global_load_dwordx4 v[190:193], v160, s[60:61]
	global_load_dwordx4 v[230:233], v19, s[62:63]
	s_add_u32 s60, s60, 0x51000
	s_addc_u32 s61, s61, 0
	s_add_u32 s62, s62, 0x10000
	s_addc_u32 s63, s63, 0
	global_load_dwordx4 v[194:197], v160, s[60:61]
	global_load_dwordx4 v[234:237], v19, s[62:63]
	s_add_u32 s60, s60, 0x51000
	s_addc_u32 s61, s61, 0
	s_add_u32 s62, s62, 0x10000
	s_addc_u32 s63, s63, 0
	global_load_dwordx4 v[198:201], v160, s[60:61]
	global_load_dwordx4 v[238:241], v19, s[62:63]
	s_add_u32 s60, s60, 0x51000
	s_addc_u32 s61, s61, 0
	s_add_u32 s62, s62, 0x10000
	s_addc_u32 s63, s63, 0
	s_mov_b32 s57, 0
; __device__ __forceinline__ float sigmoid_f(float x) { return 1.f / (1.f + __expf(-x)); }
; template <int NT, int BM, int BN, bool PLAIN, int NSTAGE, bool EPI_LDS>
; __device__ __forceinline__ void gemm_tile(const Params& p, const GemmDesc& g, bf16_t* lds, const int tid) {
;     ...
;     for (int i = 0; i < NIT; ++i) {
;       const int id = tid + NT * i;
;       const int row = id / PPR, pc = id % PPR;
;       u32x4 v = *(const u32x4*)(ct + row * CST + pc * 8);
;       bf16_t* op = o + (long)(m0e + row) * ldo + n0e + pc * 8;
;       if (g.epi == E_MERGE0 || g.epi == E_MERGEN) {
;         const u32x4 gt = *(const u32x4*)(((bf16_t*)(p.ws + OFF_proj)) + (long)(m0e + row) * LDP + gcol + n0e + pc * 8);
;         u32x4 pv = u32x4{0u, 0u, 0u, 0u};
;         if (g.epi == E_MERGEN) pv = *(const u32x4*)op;
; #pragma unroll
;         for (int e = 0; e < 4; ++e) {
;           const float g0 = sigmoid_f(__uint_as_float(gt[e] << 16)), g1 = sigmoid_f(__uint_as_float(gt[e] & 0xffff0000u));
;           const float a0 = __uint_as_float(v[e] << 16), a1 = __uint_as_float(v[e] & 0xffff0000u);
;           const float p0 = __uint_as_float(pv[e] << 16), p1 = __uint_as_float(pv[e] & 0xffff0000u);
;           v[e] = pack2(p0 + g0 * a0, p1 + g1 * a1);
;         }
;       }
;       *(u32x4*)op = v;
;     }
.Lmy_mergeN_loop:
	ds_read_b128 v[148:151], v18
	v_add_u32_e32 v18, 0x2200, v18
	s_waitcnt vmcnt(6)
	v_lshlrev_b32_e32 v2, 16, v186
	v_and_b32_e32 v3, 0xffff0000, v186
	v_mul_f32_e32 v2, 0xbfb8aa3b, v2
	v_mul_f32_e32 v3, 0xbfb8aa3b, v3
	v_exp_f32_e32 v2, v2
	v_exp_f32_e32 v3, v3
	s_nop 0
	v_pk_add_f32 v[2:3], v[2:3], 1.0 op_sel_hi:[1,0]
	s_nop 0
	v_div_scale_f32 v5, s[30:31], v3, v3, 1.0
	v_div_scale_f32 v4, s[30:31], v2, v2, 1.0
	v_rcp_f32_e32 v7, v5
	v_rcp_f32_e32 v6, v4
	v_fma_f32 v9, -v5, v7, 1.0
	v_fma_f32 v8, -v4, v6, 1.0
	v_fmac_f32_e32 v7, v9, v7
	v_fmac_f32_e32 v6, v8, v6
	v_div_scale_f32 v9, vcc, 1.0, v3, 1.0
	v_mul_f32_e32 v11, v9, v7
	v_fma_f32 v13, -v5, v11, v9
	v_fmac_f32_e32 v11, v13, v7
	v_fma_f32 v5, -v5, v11, v9
	v_div_fmas_f32 v5, v5, v7, v11
	v_div_fixup_f32 v3, v5, v3, 1.0
	v_div_scale_f32 v8, vcc, 1.0, v2, 1.0
	v_mul_f32_e32 v10, v8, v6
	v_fma_f32 v12, -v4, v10, v8
	v_fmac_f32_e32 v10, v12, v6
	v_fma_f32 v4, -v4, v10, v8
	v_div_fmas_f32 v4, v4, v6, v10
	v_div_fixup_f32 v2, v4, v2, 1.0
	s_waitcnt lgkmcnt(0)
	v_lshlrev_b32_e32 v14, 16, v148
	v_and_b32_e32 v15, 0xffff0000, v148
	v_lshlrev_b32_e32 v16, 16, v226
	v_and_b32_e32 v17, 0xffff0000, v226
	v_pk_fma_f32 v[2:3], v[2:3], v[14:15], v[16:17]
	s_nop 0
	v_cvt_pk_bf16_f32 v156, v2, v3
	v_lshlrev_b32_e32 v2, 16, v187
	v_and_b32_e32 v3, 0xffff0000, v187
	v_mul_f32_e32 v2, 0xbfb8aa3b, v2
	v_mul_f32_e32 v3, 0xbfb8aa3b, v3
	v_exp_f32_e32 v2, v2
	v_exp_f32_e32 v3, v3
	s_nop 0
	v_pk_add_f32 v[2:3], v[2:3], 1.0 op_sel_hi:[1,0]
	s_nop 0
	v_div_scale_f32 v5, s[30:31], v3, v3, 1.0
	v_div_scale_f32 v4, s[30:31], v2, v2, 1.0
	v_rcp_f32_e32 v7, v5
	v_rcp_f32_e32 v6, v4
	v_fma_f32 v9, -v5, v7, 1.0
	v_fma_f32 v8, -v4, v6, 1.0
	v_fmac_f32_e32 v7, v9, v7
	v_fmac_f32_e32 v6, v8, v6
	v_div_scale_f32 v9, vcc, 1.0, v3, 1.0
	v_mul_f32_e32 v11, v9, v7
	v_fma_f32 v13, -v5, v11, v9
	v_fmac_f32_e32 v11, v13, v7
	v_fma_f32 v5, -v5, v11, v9
	v_div_fmas_f32 v5, v5, v7, v11
	v_div_fixup_f32 v3, v5, v3, 1.0
	v_div_scale_f32 v8, vcc, 1.0, v2, 1.0
	v_mul_f32_e32 v10, v8, v6
	v_fma_f32 v12, -v4, v10, v8
	v_fmac_f32_e32 v10, v12, v6
	v_fma_f32 v4, -v4, v10, v8
	v_div_fmas_f32 v4, v4, v6, v10
	v_div_fixup_f32 v2, v4, v2, 1.0
	v_lshlrev_b32_e32 v14, 16, v149
	v_and_b32_e32 v15, 0xffff0000, v149
	v_lshlrev_b32_e32 v16, 16, v227
	v_and_b32_e32 v17, 0xffff0000, v227
	v_pk_fma_f32 v[2:3], v[2:3], v[14:15], v[16:17]
	s_nop 0
	v_cvt_pk_bf16_f32 v157, v2, v3
	v_lshlrev_b32_e32 v2, 16, v188
	v_and_b32_e32 v3, 0xffff0000, v188
	v_mul_f32_e32 v2, 0xbfb8aa3b, v2
	v_mul_f32_e32 v3, 0xbfb8aa3b, v3
	v_exp_f32_e32 v2, v2
	v_exp_f32_e32 v3, v3
	s_nop 0
	v_pk_add_f32 v[2:3], v[2:3], 1.0 op_sel_hi:[1,0]
	s_nop 0
	v_div_scale_f32 v5, s[30:31], v3, v3, 1.0
	v_div_scale_f32 v4, s[30:31], v2, v2, 1.0
	v_rcp_f32_e32 v7, v5
	v_rcp_f32_e32 v6, v4
	v_fma_f32 v9, -v5, v7, 1.0
	v_fma_f32 v8, -v4, v6, 1.0
	v_fmac_f32_e32 v7, v9, v7
	v_fmac_f32_e32 v6, v8, v6
	v_div_scale_f32 v9, vcc, 1.0, v3, 1.0
	v_mul_f32_e32 v11, v9, v7
	v_fma_f32 v13, -v5, v11, v9
	v_fmac_f32_e32 v11, v13, v7
	v_fma_f32 v5, -v5, v11, v9
	v_div_fmas_f32 v5, v5, v7, v11
	v_div_fixup_f32 v3, v5, v3, 1.0
	v_div_scale_f32 v8, vcc, 1.0, v2, 1.0
	v_mul_f32_e32 v10, v8, v6
	v_fma_f32 v12, -v4, v10, v8
	v_fmac_f32_e32 v10, v12, v6
	v_fma_f32 v4, -v4, v10, v8
	v_div_fmas_f32 v4, v4, v6, v10
	v_div_fixup_f32 v2, v4, v2, 1.0
	v_lshlrev_b32_e32 v14, 16, v150
	v_and_b32_e32 v15, 0xffff0000, v150
	v_lshlrev_b32_e32 v16, 16, v228
	v_and_b32_e32 v17, 0xffff0000, v228
	v_pk_fma_f32 v[2:3], v[2:3], v[14:15], v[16:17]
	s_nop 0
	v_cvt_pk_bf16_f32 v158, v2, v3
	v_lshlrev_b32_e32 v2, 16, v189
	v_and_b32_e32 v3, 0xffff0000, v189
	v_mul_f32_e32 v2, 0xbfb8aa3b, v2
	v_mul_f32_e32 v3, 0xbfb8aa3b, v3
	v_exp_f32_e32 v2, v2
	v_exp_f32_e32 v3, v3
	s_nop 0
	v_pk_add_f32 v[2:3], v[2:3], 1.0 op_sel_hi:[1,0]
	s_nop 0
	v_div_scale_f32 v5, s[30:31], v3, v3, 1.0
	v_div_scale_f32 v4, s[30:31], v2, v2, 1.0
	v_rcp_f32_e32 v7, v5
	v_rcp_f32_e32 v6, v4
	v_fma_f32 v9, -v5, v7, 1.0
	v_fma_f32 v8, -v4, v6, 1.0
	v_fmac_f32_e32 v7, v9, v7
	v_fmac_f32_e32 v6, v8, v6
	v_div_scale_f32 v9, vcc, 1.0, v3, 1.0
	v_mul_f32_e32 v11, v9, v7
	v_fma_f32 v13, -v5, v11, v9
	v_fmac_f32_e32 v11, v13, v7
	v_fma_f32 v5, -v5, v11, v9
	v_div_fmas_f32 v5, v5, v7, v11
	v_div_fixup_f32 v3, v5, v3, 1.0
	v_div_scale_f32 v8, vcc, 1.0, v2, 1.0
	v_mul_f32_e32 v10, v8, v6
	v_fma_f32 v12, -v4, v10, v8
	v_fmac_f32_e32 v10, v12, v6
	v_fma_f32 v4, -v4, v10, v8
	v_div_fmas_f32 v4, v4, v6, v10
	v_div_fixup_f32 v2, v4, v2, 1.0
	v_lshlrev_b32_e32 v14, 16, v151
	v_and_b32_e32 v15, 0xffff0000, v151
	v_lshlrev_b32_e32 v16, 16, v229
	v_and_b32_e32 v17, 0xffff0000, v229
	v_pk_fma_f32 v[2:3], v[2:3], v[14:15], v[16:17]
	s_nop 0
	v_cvt_pk_bf16_f32 v159, v2, v3
	global_load_dwordx4 v[186:189], v160, s[60:61]
	global_load_dwordx4 v[226:229], v19, s[62:63]
	s_add_u32 s60, s60, 0x51000
	s_addc_u32 s61, s61, 0
	s_add_u32 s62, s62, 0x10000
	s_addc_u32 s63, s63, 0
	global_store_dwordx4 v19, v[156:159], s[64:65]
	s_add_u32 s64, s64, 0x10000
	s_addc_u32 s65, s65, 0
	ds_read_b128 v[148:151], v18
	v_add_u32_e32 v18, 0x2200, v18
	s_waitcnt vmcnt(7)
	v_lshlrev_b32_e32 v2, 16, v190
	v_and_b32_e32 v3, 0xffff0000, v190
	v_mul_f32_e32 v2, 0xbfb8aa3b, v2
	v_mul_f32_e32 v3, 0xbfb8aa3b, v3
	v_exp_f32_e32 v2, v2
	v_exp_f32_e32 v3, v3
	s_nop 0
	v_pk_add_f32 v[2:3], v[2:3], 1.0 op_sel_hi:[1,0]
	s_nop 0
	v_div_scale_f32 v5, s[30:31], v3, v3, 1.0
	v_div_scale_f32 v4, s[30:31], v2, v2, 1.0
	v_rcp_f32_e32 v7, v5
	v_rcp_f32_e32 v6, v4
	v_fma_f32 v9, -v5, v7, 1.0
	v_fma_f32 v8, -v4, v6, 1.0
	v_fmac_f32_e32 v7, v9, v7
	v_fmac_f32_e32 v6, v8, v6
	v_div_scale_f32 v9, vcc, 1.0, v3, 1.0
	v_mul_f32_e32 v11, v9, v7
	v_fma_f32 v13, -v5, v11, v9
	v_fmac_f32_e32 v11, v13, v7
	v_fma_f32 v5, -v5, v11, v9
	v_div_fmas_f32 v5, v5, v7, v11
	v_div_fixup_f32 v3, v5, v3, 1.0
	v_div_scale_f32 v8, vcc, 1.0, v2, 1.0
	v_mul_f32_e32 v10, v8, v6
	v_fma_f32 v12, -v4, v10, v8
	v_fmac_f32_e32 v10, v12, v6
	v_fma_f32 v4, -v4, v10, v8
	v_div_fmas_f32 v4, v4, v6, v10
	v_div_fixup_f32 v2, v4, v2, 1.0
	s_waitcnt lgkmcnt(0)
; __device__ __forceinline__ float sigmoid_f(float x) { return 1.f / (1.f + __expf(-x)); }
; template <int NT, int BM, int BN, bool PLAIN, int NSTAGE, bool EPI_LDS>
; __device__ __forceinline__ void gemm_tile(const Params& p, const GemmDesc& g, bf16_t* lds, const int tid) {
;     ...
;     for (int i = 0; i < NIT; ++i) {
;       const int id = tid + NT * i;
;       const int row = id / PPR, pc = id % PPR;
;       u32x4 v = *(const u32x4*)(ct + row * CST + pc * 8);
;       bf16_t* op = o + (long)(m0e + row) * ldo + n0e + pc * 8;
;       if (g.epi == E_MERGE0 || g.epi == E_MERGEN) {
;         const u32x4 gt = *(const u32x4*)(((bf16_t*)(p.ws + OFF_proj)) + (long)(m0e + row) * LDP + gcol + n0e + pc * 8);
;         u32x4 pv = u32x4{0u, 0u, 0u, 0u};
;         if (g.epi == E_MERGEN) pv = *(const u32x4*)op;
; #pragma unroll
;         for (int e = 0; e < 4; ++e) {
;           const float g0 = sigmoid_f(__uint_as_float(gt[e] << 16)), g1 = sigmoid_f(__uint_as_float(gt[e] & 0xffff0000u));
;           const float a0 = __uint_as_float(v[e] << 16), a1 = __uint_as_float(v[e] & 0xffff0000u);
;           const float p0 = __uint_as_float(pv[e] << 16), p1 = __uint_as_float(pv[e] & 0xffff0000u);
;           v[e] = pack2(p0 + g0 * a0, p1 + g1 * a1);
;         }
;       }
;       *(u32x4*)op = v;
;     }
	v_lshlrev_b32_e32 v14, 16, v148
	v_and_b32_e32 v15, 0xffff0000, v148
	v_lshlrev_b32_e32 v16, 16, v230
	v_and_b32_e32 v17, 0xffff0000, v230
	v_pk_fma_f32 v[2:3], v[2:3], v[14:15], v[16:17]
	s_nop 0
	v_cvt_pk_bf16_f32 v156, v2, v3
	v_lshlrev_b32_e32 v2, 16, v191
	v_and_b32_e32 v3, 0xffff0000, v191
	v_mul_f32_e32 v2, 0xbfb8aa3b, v2
	v_mul_f32_e32 v3, 0xbfb8aa3b, v3
	v_exp_f32_e32 v2, v2
	v_exp_f32_e32 v3, v3
	s_nop 0
	v_pk_add_f32 v[2:3], v[2:3], 1.0 op_sel_hi:[1,0]
	s_nop 0
	v_div_scale_f32 v5, s[30:31], v3, v3, 1.0
	v_div_scale_f32 v4, s[30:31], v2, v2, 1.0
	v_rcp_f32_e32 v7, v5
	v_rcp_f32_e32 v6, v4
	v_fma_f32 v9, -v5, v7, 1.0
	v_fma_f32 v8, -v4, v6, 1.0
	v_fmac_f32_e32 v7, v9, v7
	v_fmac_f32_e32 v6, v8, v6
	v_div_scale_f32 v9, vcc, 1.0, v3, 1.0
	v_mul_f32_e32 v11, v9, v7
	v_fma_f32 v13, -v5, v11, v9
	v_fmac_f32_e32 v11, v13, v7
	v_fma_f32 v5, -v5, v11, v9
	v_div_fmas_f32 v5, v5, v7, v11
	v_div_fixup_f32 v3, v5, v3, 1.0
	v_div_scale_f32 v8, vcc, 1.0, v2, 1.0
	v_mul_f32_e32 v10, v8, v6
	v_fma_f32 v12, -v4, v10, v8
	v_fmac_f32_e32 v10, v12, v6
	v_fma_f32 v4, -v4, v10, v8
	v_div_fmas_f32 v4, v4, v6, v10
	v_div_fixup_f32 v2, v4, v2, 1.0
	v_lshlrev_b32_e32 v14, 16, v149
	v_and_b32_e32 v15, 0xffff0000, v149
	v_lshlrev_b32_e32 v16, 16, v231
	v_and_b32_e32 v17, 0xffff0000, v231
	v_pk_fma_f32 v[2:3], v[2:3], v[14:15], v[16:17]
	s_nop 0
	v_cvt_pk_bf16_f32 v157, v2, v3
	v_lshlrev_b32_e32 v2, 16, v192
	v_and_b32_e32 v3, 0xffff0000, v192
	v_mul_f32_e32 v2, 0xbfb8aa3b, v2
	v_mul_f32_e32 v3, 0xbfb8aa3b, v3
	v_exp_f32_e32 v2, v2
	v_exp_f32_e32 v3, v3
	s_nop 0
	v_pk_add_f32 v[2:3], v[2:3], 1.0 op_sel_hi:[1,0]
	s_nop 0
	v_div_scale_f32 v5, s[30:31], v3, v3, 1.0
	v_div_scale_f32 v4, s[30:31], v2, v2, 1.0
	v_rcp_f32_e32 v7, v5
	v_rcp_f32_e32 v6, v4
	v_fma_f32 v9, -v5, v7, 1.0
	v_fma_f32 v8, -v4, v6, 1.0
	v_fmac_f32_e32 v7, v9, v7
	v_fmac_f32_e32 v6, v8, v6
	v_div_scale_f32 v9, vcc, 1.0, v3, 1.0
	v_mul_f32_e32 v11, v9, v7
	v_fma_f32 v13, -v5, v11, v9
	v_fmac_f32_e32 v11, v13, v7
	v_fma_f32 v5, -v5, v11, v9
	v_div_fmas_f32 v5, v5, v7, v11
	v_div_fixup_f32 v3, v5, v3, 1.0
	v_div_scale_f32 v8, vcc, 1.0, v2, 1.0
	v_mul_f32_e32 v10, v8, v6
	v_fma_f32 v12, -v4, v10, v8
	v_fmac_f32_e32 v10, v12, v6
	v_fma_f32 v4, -v4, v10, v8
	v_div_fmas_f32 v4, v4, v6, v10
	v_div_fixup_f32 v2, v4, v2, 1.0
	v_lshlrev_b32_e32 v14, 16, v150
	v_and_b32_e32 v15, 0xffff0000, v150
	v_lshlrev_b32_e32 v16, 16, v232
	v_and_b32_e32 v17, 0xffff0000, v232
	v_pk_fma_f32 v[2:3], v[2:3], v[14:15], v[16:17]
	s_nop 0
	v_cvt_pk_bf16_f32 v158, v2, v3
	v_lshlrev_b32_e32 v2, 16, v193
	v_and_b32_e32 v3, 0xffff0000, v193
	v_mul_f32_e32 v2, 0xbfb8aa3b, v2
	v_mul_f32_e32 v3, 0xbfb8aa3b, v3
	v_exp_f32_e32 v2, v2
	v_exp_f32_e32 v3, v3
	s_nop 0
	v_pk_add_f32 v[2:3], v[2:3], 1.0 op_sel_hi:[1,0]
	s_nop 0
	v_div_scale_f32 v5, s[30:31], v3, v3, 1.0
	v_div_scale_f32 v4, s[30:31], v2, v2, 1.0
	v_rcp_f32_e32 v7, v5
	v_rcp_f32_e32 v6, v4
	v_fma_f32 v9, -v5, v7, 1.0
	v_fma_f32 v8, -v4, v6, 1.0
	v_fmac_f32_e32 v7, v9, v7
	v_fmac_f32_e32 v6, v8, v6
	v_div_scale_f32 v9, vcc, 1.0, v3, 1.0
	v_mul_f32_e32 v11, v9, v7
	v_fma_f32 v13, -v5, v11, v9
	v_fmac_f32_e32 v11, v13, v7
	v_fma_f32 v5, -v5, v11, v9
	v_div_fmas_f32 v5, v5, v7, v11
	v_div_fixup_f32 v3, v5, v3, 1.0
	v_div_scale_f32 v8, vcc, 1.0, v2, 1.0
	v_mul_f32_e32 v10, v8, v6
	v_fma_f32 v12, -v4, v10, v8
	v_fmac_f32_e32 v10, v12, v6
	v_fma_f32 v4, -v4, v10, v8
	v_div_fmas_f32 v4, v4, v6, v10
	v_div_fixup_f32 v2, v4, v2, 1.0
	v_lshlrev_b32_e32 v14, 16, v151
	v_and_b32_e32 v15, 0xffff0000, v151
	v_lshlrev_b32_e32 v16, 16, v233
	v_and_b32_e32 v17, 0xffff0000, v233
	v_pk_fma_f32 v[2:3], v[2:3], v[14:15], v[16:17]
	s_nop 0
	v_cvt_pk_bf16_f32 v159, v2, v3
	global_load_dwordx4 v[190:193], v160, s[60:61]
	global_load_dwordx4 v[230:233], v19, s[62:63]
	s_add_u32 s60, s60, 0x51000
	s_addc_u32 s61, s61, 0
	s_add_u32 s62, s62, 0x10000
	s_addc_u32 s63, s63, 0
	global_store_dwordx4 v19, v[156:159], s[64:65]
	s_add_u32 s64, s64, 0x10000
	s_addc_u32 s65, s65, 0
	ds_read_b128 v[148:151], v18
	v_add_u32_e32 v18, 0x2200, v18
	s_waitcnt vmcnt(8)
	v_lshlrev_b32_e32 v2, 16, v194
	v_and_b32_e32 v3, 0xffff0000, v194
	v_mul_f32_e32 v2, 0xbfb8aa3b, v2
	v_mul_f32_e32 v3, 0xbfb8aa3b, v3
	v_exp_f32_e32 v2, v2
	v_exp_f32_e32 v3, v3
	s_nop 0
	v_pk_add_f32 v[2:3], v[2:3], 1.0 op_sel_hi:[1,0]
	s_nop 0
	v_div_scale_f32 v5, s[30:31], v3, v3, 1.0
	v_div_scale_f32 v4, s[30:31], v2, v2, 1.0
	v_rcp_f32_e32 v7, v5
	v_rcp_f32_e32 v6, v4
	v_fma_f32 v9, -v5, v7, 1.0
	v_fma_f32 v8, -v4, v6, 1.0
	v_fmac_f32_e32 v7, v9, v7
	v_fmac_f32_e32 v6, v8, v6
	v_div_scale_f32 v9, vcc, 1.0, v3, 1.0
	v_mul_f32_e32 v11, v9, v7
	v_fma_f32 v13, -v5, v11, v9
	v_fmac_f32_e32 v11, v13, v7
	v_fma_f32 v5, -v5, v11, v9
	v_div_fmas_f32 v5, v5, v7, v11
	v_div_fixup_f32 v3, v5, v3, 1.0
	v_div_scale_f32 v8, vcc, 1.0, v2, 1.0
	v_mul_f32_e32 v10, v8, v6
	v_fma_f32 v12, -v4, v10, v8
	v_fmac_f32_e32 v10, v12, v6
	v_fma_f32 v4, -v4, v10, v8
	v_div_fmas_f32 v4, v4, v6, v10
	v_div_fixup_f32 v2, v4, v2, 1.0
	s_waitcnt lgkmcnt(0)
; __device__ __forceinline__ float sigmoid_f(float x) { return 1.f / (1.f + __expf(-x)); }
; template <int NT, int BM, int BN, bool PLAIN, int NSTAGE, bool EPI_LDS>
; __device__ __forceinline__ void gemm_tile(const Params& p, const GemmDesc& g, bf16_t* lds, const int tid) {
;     ...
;     for (int i = 0; i < NIT; ++i) {
;       const int id = tid + NT * i;
;       const int row = id / PPR, pc = id % PPR;
;       u32x4 v = *(const u32x4*)(ct + row * CST + pc * 8);
;       bf16_t* op = o + (long)(m0e + row) * ldo + n0e + pc * 8;
;       if (g.epi == E_MERGE0 || g.epi == E_MERGEN) {
;         const u32x4 gt = *(const u32x4*)(((bf16_t*)(p.ws + OFF_proj)) + (long)(m0e + row) * LDP + gcol + n0e + pc * 8);
;         u32x4 pv = u32x4{0u, 0u, 0u, 0u};
;         if (g.epi == E_MERGEN) pv = *(const u32x4*)op;
; #pragma unroll
;         for (int e = 0; e < 4; ++e) {
;           const float g0 = sigmoid_f(__uint_as_float(gt[e] << 16)), g1 = sigmoid_f(__uint_as_float(gt[e] & 0xffff0000u));
;           const float a0 = __uint_as_float(v[e] << 16), a1 = __uint_as_float(v[e] & 0xffff0000u);
;           const float p0 = __uint_as_float(pv[e] << 16), p1 = __uint_as_float(pv[e] & 0xffff0000u);
;           v[e] = pack2(p0 + g0 * a0, p1 + g1 * a1);
;         }
;       }
;       *(u32x4*)op = v;
;     }
	v_lshlrev_b32_e32 v14, 16, v148
	v_and_b32_e32 v15, 0xffff0000, v148
	v_lshlrev_b32_e32 v16, 16, v234
	v_and_b32_e32 v17, 0xffff0000, v234
	v_pk_fma_f32 v[2:3], v[2:3], v[14:15], v[16:17]
	s_nop 0
	v_cvt_pk_bf16_f32 v156, v2, v3
	v_lshlrev_b32_e32 v2, 16, v195
	v_and_b32_e32 v3, 0xffff0000, v195
	v_mul_f32_e32 v2, 0xbfb8aa3b, v2
	v_mul_f32_e32 v3, 0xbfb8aa3b, v3
	v_exp_f32_e32 v2, v2
	v_exp_f32_e32 v3, v3
	s_nop 0
	v_pk_add_f32 v[2:3], v[2:3], 1.0 op_sel_hi:[1,0]
	s_nop 0
	v_div_scale_f32 v5, s[30:31], v3, v3, 1.0
	v_div_scale_f32 v4, s[30:31], v2, v2, 1.0
	v_rcp_f32_e32 v7, v5
	v_rcp_f32_e32 v6, v4
	v_fma_f32 v9, -v5, v7, 1.0
	v_fma_f32 v8, -v4, v6, 1.0
	v_fmac_f32_e32 v7, v9, v7
	v_fmac_f32_e32 v6, v8, v6
	v_div_scale_f32 v9, vcc, 1.0, v3, 1.0
	v_mul_f32_e32 v11, v9, v7
	v_fma_f32 v13, -v5, v11, v9
	v_fmac_f32_e32 v11, v13, v7
	v_fma_f32 v5, -v5, v11, v9
	v_div_fmas_f32 v5, v5, v7, v11
	v_div_fixup_f32 v3, v5, v3, 1.0
	v_div_scale_f32 v8, vcc, 1.0, v2, 1.0
	v_mul_f32_e32 v10, v8, v6
	v_fma_f32 v12, -v4, v10, v8
	v_fmac_f32_e32 v10, v12, v6
	v_fma_f32 v4, -v4, v10, v8
	v_div_fmas_f32 v4, v4, v6, v10
	v_div_fixup_f32 v2, v4, v2, 1.0
	v_lshlrev_b32_e32 v14, 16, v149
	v_and_b32_e32 v15, 0xffff0000, v149
	v_lshlrev_b32_e32 v16, 16, v235
	v_and_b32_e32 v17, 0xffff0000, v235
	v_pk_fma_f32 v[2:3], v[2:3], v[14:15], v[16:17]
	s_nop 0
	v_cvt_pk_bf16_f32 v157, v2, v3
	v_lshlrev_b32_e32 v2, 16, v196
	v_and_b32_e32 v3, 0xffff0000, v196
	v_mul_f32_e32 v2, 0xbfb8aa3b, v2
	v_mul_f32_e32 v3, 0xbfb8aa3b, v3
	v_exp_f32_e32 v2, v2
	v_exp_f32_e32 v3, v3
	s_nop 0
	v_pk_add_f32 v[2:3], v[2:3], 1.0 op_sel_hi:[1,0]
	s_nop 0
	v_div_scale_f32 v5, s[30:31], v3, v3, 1.0
	v_div_scale_f32 v4, s[30:31], v2, v2, 1.0
	v_rcp_f32_e32 v7, v5
	v_rcp_f32_e32 v6, v4
	v_fma_f32 v9, -v5, v7, 1.0
	v_fma_f32 v8, -v4, v6, 1.0
	v_fmac_f32_e32 v7, v9, v7
	v_fmac_f32_e32 v6, v8, v6
	v_div_scale_f32 v9, vcc, 1.0, v3, 1.0
	v_mul_f32_e32 v11, v9, v7
	v_fma_f32 v13, -v5, v11, v9
	v_fmac_f32_e32 v11, v13, v7
	v_fma_f32 v5, -v5, v11, v9
	v_div_fmas_f32 v5, v5, v7, v11
	v_div_fixup_f32 v3, v5, v3, 1.0
	v_div_scale_f32 v8, vcc, 1.0, v2, 1.0
	v_mul_f32_e32 v10, v8, v6
	v_fma_f32 v12, -v4, v10, v8
	v_fmac_f32_e32 v10, v12, v6
	v_fma_f32 v4, -v4, v10, v8
	v_div_fmas_f32 v4, v4, v6, v10
	v_div_fixup_f32 v2, v4, v2, 1.0
	v_lshlrev_b32_e32 v14, 16, v150
	v_and_b32_e32 v15, 0xffff0000, v150
	v_lshlrev_b32_e32 v16, 16, v236
	v_and_b32_e32 v17, 0xffff0000, v236
	v_pk_fma_f32 v[2:3], v[2:3], v[14:15], v[16:17]
	s_nop 0
	v_cvt_pk_bf16_f32 v158, v2, v3
	v_lshlrev_b32_e32 v2, 16, v197
	v_and_b32_e32 v3, 0xffff0000, v197
	v_mul_f32_e32 v2, 0xbfb8aa3b, v2
	v_mul_f32_e32 v3, 0xbfb8aa3b, v3
	v_exp_f32_e32 v2, v2
	v_exp_f32_e32 v3, v3
	s_nop 0
	v_pk_add_f32 v[2:3], v[2:3], 1.0 op_sel_hi:[1,0]
	s_nop 0
	v_div_scale_f32 v5, s[30:31], v3, v3, 1.0
	v_div_scale_f32 v4, s[30:31], v2, v2, 1.0
	v_rcp_f32_e32 v7, v5
	v_rcp_f32_e32 v6, v4
	v_fma_f32 v9, -v5, v7, 1.0
	v_fma_f32 v8, -v4, v6, 1.0
	v_fmac_f32_e32 v7, v9, v7
	v_fmac_f32_e32 v6, v8, v6
	v_div_scale_f32 v9, vcc, 1.0, v3, 1.0
	v_mul_f32_e32 v11, v9, v7
	v_fma_f32 v13, -v5, v11, v9
	v_fmac_f32_e32 v11, v13, v7
	v_fma_f32 v5, -v5, v11, v9
	v_div_fmas_f32 v5, v5, v7, v11
	v_div_fixup_f32 v3, v5, v3, 1.0
	v_div_scale_f32 v8, vcc, 1.0, v2, 1.0
	v_mul_f32_e32 v10, v8, v6
	v_fma_f32 v12, -v4, v10, v8
	v_fmac_f32_e32 v10, v12, v6
	v_fma_f32 v4, -v4, v10, v8
	v_div_fmas_f32 v4, v4, v6, v10
	v_div_fixup_f32 v2, v4, v2, 1.0
	v_lshlrev_b32_e32 v14, 16, v151
	v_and_b32_e32 v15, 0xffff0000, v151
	v_lshlrev_b32_e32 v16, 16, v237
	v_and_b32_e32 v17, 0xffff0000, v237
	v_pk_fma_f32 v[2:3], v[2:3], v[14:15], v[16:17]
	s_nop 0
	v_cvt_pk_bf16_f32 v159, v2, v3
	global_load_dwordx4 v[194:197], v160, s[60:61]
	global_load_dwordx4 v[234:237], v19, s[62:63]
	s_add_u32 s60, s60, 0x51000
	s_addc_u32 s61, s61, 0
	s_add_u32 s62, s62, 0x10000
	s_addc_u32 s63, s63, 0
	global_store_dwordx4 v19, v[156:159], s[64:65]
	s_add_u32 s64, s64, 0x10000
	s_addc_u32 s65, s65, 0
	ds_read_b128 v[148:151], v18
	v_add_u32_e32 v18, 0x2200, v18
	s_waitcnt vmcnt(9)
	v_lshlrev_b32_e32 v2, 16, v198
	v_and_b32_e32 v3, 0xffff0000, v198
	v_mul_f32_e32 v2, 0xbfb8aa3b, v2
	v_mul_f32_e32 v3, 0xbfb8aa3b, v3
	v_exp_f32_e32 v2, v2
	v_exp_f32_e32 v3, v3
	s_nop 0
	v_pk_add_f32 v[2:3], v[2:3], 1.0 op_sel_hi:[1,0]
	s_nop 0
	v_div_scale_f32 v5, s[30:31], v3, v3, 1.0
	v_div_scale_f32 v4, s[30:31], v2, v2, 1.0
	v_rcp_f32_e32 v7, v5
	v_rcp_f32_e32 v6, v4
	v_fma_f32 v9, -v5, v7, 1.0
	v_fma_f32 v8, -v4, v6, 1.0
	v_fmac_f32_e32 v7, v9, v7
	v_fmac_f32_e32 v6, v8, v6
	v_div_scale_f32 v9, vcc, 1.0, v3, 1.0
	v_mul_f32_e32 v11, v9, v7
	v_fma_f32 v13, -v5, v11, v9
	v_fmac_f32_e32 v11, v13, v7
	v_fma_f32 v5, -v5, v11, v9
	v_div_fmas_f32 v5, v5, v7, v11
	v_div_fixup_f32 v3, v5, v3, 1.0
	v_div_scale_f32 v8, vcc, 1.0, v2, 1.0
	v_mul_f32_e32 v10, v8, v6
	v_fma_f32 v12, -v4, v10, v8
	v_fmac_f32_e32 v10, v12, v6
	v_fma_f32 v4, -v4, v10, v8
	v_div_fmas_f32 v4, v4, v6, v10
	v_div_fixup_f32 v2, v4, v2, 1.0
	s_waitcnt lgkmcnt(0)
; __device__ __forceinline__ float sigmoid_f(float x) { return 1.f / (1.f + __expf(-x)); }
; template <int NT, int BM, int BN, bool PLAIN, int NSTAGE, bool EPI_LDS>
; __device__ __forceinline__ void gemm_tile(const Params& p, const GemmDesc& g, bf16_t* lds, const int tid) {
;     ...
;     for (int i = 0; i < NIT; ++i) {
;       const int id = tid + NT * i;
;       const int row = id / PPR, pc = id % PPR;
;       u32x4 v = *(const u32x4*)(ct + row * CST + pc * 8);
;       bf16_t* op = o + (long)(m0e + row) * ldo + n0e + pc * 8;
;       if (g.epi == E_MERGE0 || g.epi == E_MERGEN) {
;         const u32x4 gt = *(const u32x4*)(((bf16_t*)(p.ws + OFF_proj)) + (long)(m0e + row) * LDP + gcol + n0e + pc * 8);
;         u32x4 pv = u32x4{0u, 0u, 0u, 0u};
;         if (g.epi == E_MERGEN) pv = *(const u32x4*)op;
; #pragma unroll
;         for (int e = 0; e < 4; ++e) {
;           const float g0 = sigmoid_f(__uint_as_float(gt[e] << 16)), g1 = sigmoid_f(__uint_as_float(gt[e] & 0xffff0000u));
;           const float a0 = __uint_as_float(v[e] << 16), a1 = __uint_as_float(v[e] & 0xffff0000u);
;           const float p0 = __uint_as_float(pv[e] << 16), p1 = __uint_as_float(pv[e] & 0xffff0000u);
;           v[e] = pack2(p0 + g0 * a0, p1 + g1 * a1);
;         }
;       }
;       *(u32x4*)op = v;
;     }
	v_lshlrev_b32_e32 v14, 16, v148
	v_and_b32_e32 v15, 0xffff0000, v148
	v_lshlrev_b32_e32 v16, 16, v238
	v_and_b32_e32 v17, 0xffff0000, v238
	v_pk_fma_f32 v[2:3], v[2:3], v[14:15], v[16:17]
	s_nop 0
	v_cvt_pk_bf16_f32 v156, v2, v3
	v_lshlrev_b32_e32 v2, 16, v199
	v_and_b32_e32 v3, 0xffff0000, v199
	v_mul_f32_e32 v2, 0xbfb8aa3b, v2
	v_mul_f32_e32 v3, 0xbfb8aa3b, v3
	v_exp_f32_e32 v2, v2
	v_exp_f32_e32 v3, v3
	s_nop 0
	v_pk_add_f32 v[2:3], v[2:3], 1.0 op_sel_hi:[1,0]
	s_nop 0
	v_div_scale_f32 v5, s[30:31], v3, v3, 1.0
	v_div_scale_f32 v4, s[30:31], v2, v2, 1.0
	v_rcp_f32_e32 v7, v5
	v_rcp_f32_e32 v6, v4
	v_fma_f32 v9, -v5, v7, 1.0
	v_fma_f32 v8, -v4, v6, 1.0
	v_fmac_f32_e32 v7, v9, v7
	v_fmac_f32_e32 v6, v8, v6
	v_div_scale_f32 v9, vcc, 1.0, v3, 1.0
	v_mul_f32_e32 v11, v9, v7
	v_fma_f32 v13, -v5, v11, v9
	v_fmac_f32_e32 v11, v13, v7
	v_fma_f32 v5, -v5, v11, v9
	v_div_fmas_f32 v5, v5, v7, v11
	v_div_fixup_f32 v3, v5, v3, 1.0
	v_div_scale_f32 v8, vcc, 1.0, v2, 1.0
	v_mul_f32_e32 v10, v8, v6
	v_fma_f32 v12, -v4, v10, v8
	v_fmac_f32_e32 v10, v12, v6
	v_fma_f32 v4, -v4, v10, v8
	v_div_fmas_f32 v4, v4, v6, v10
	v_div_fixup_f32 v2, v4, v2, 1.0
	v_lshlrev_b32_e32 v14, 16, v149
	v_and_b32_e32 v15, 0xffff0000, v149
	v_lshlrev_b32_e32 v16, 16, v239
	v_and_b32_e32 v17, 0xffff0000, v239
	v_pk_fma_f32 v[2:3], v[2:3], v[14:15], v[16:17]
	s_nop 0
	v_cvt_pk_bf16_f32 v157, v2, v3
	v_lshlrev_b32_e32 v2, 16, v200
	v_and_b32_e32 v3, 0xffff0000, v200
	v_mul_f32_e32 v2, 0xbfb8aa3b, v2
	v_mul_f32_e32 v3, 0xbfb8aa3b, v3
	v_exp_f32_e32 v2, v2
	v_exp_f32_e32 v3, v3
	s_nop 0
	v_pk_add_f32 v[2:3], v[2:3], 1.0 op_sel_hi:[1,0]
	s_nop 0
	v_div_scale_f32 v5, s[30:31], v3, v3, 1.0
	v_div_scale_f32 v4, s[30:31], v2, v2, 1.0
	v_rcp_f32_e32 v7, v5
	v_rcp_f32_e32 v6, v4
	v_fma_f32 v9, -v5, v7, 1.0
	v_fma_f32 v8, -v4, v6, 1.0
	v_fmac_f32_e32 v7, v9, v7
	v_fmac_f32_e32 v6, v8, v6
	v_div_scale_f32 v9, vcc, 1.0, v3, 1.0
	v_mul_f32_e32 v11, v9, v7
	v_fma_f32 v13, -v5, v11, v9
	v_fmac_f32_e32 v11, v13, v7
	v_fma_f32 v5, -v5, v11, v9
	v_div_fmas_f32 v5, v5, v7, v11
	v_div_fixup_f32 v3, v5, v3, 1.0
	v_div_scale_f32 v8, vcc, 1.0, v2, 1.0
	v_mul_f32_e32 v10, v8, v6
	v_fma_f32 v12, -v4, v10, v8
	v_fmac_f32_e32 v10, v12, v6
	v_fma_f32 v4, -v4, v10, v8
	v_div_fmas_f32 v4, v4, v6, v10
	v_div_fixup_f32 v2, v4, v2, 1.0
	v_lshlrev_b32_e32 v14, 16, v150
	v_and_b32_e32 v15, 0xffff0000, v150
	v_lshlrev_b32_e32 v16, 16, v240
	v_and_b32_e32 v17, 0xffff0000, v240
	v_pk_fma_f32 v[2:3], v[2:3], v[14:15], v[16:17]
	s_nop 0
	v_cvt_pk_bf16_f32 v158, v2, v3
	v_lshlrev_b32_e32 v2, 16, v201
	v_and_b32_e32 v3, 0xffff0000, v201
	v_mul_f32_e32 v2, 0xbfb8aa3b, v2
	v_mul_f32_e32 v3, 0xbfb8aa3b, v3
	v_exp_f32_e32 v2, v2
	v_exp_f32_e32 v3, v3
	s_nop 0
	v_pk_add_f32 v[2:3], v[2:3], 1.0 op_sel_hi:[1,0]
	s_nop 0
	v_div_scale_f32 v5, s[30:31], v3, v3, 1.0
	v_div_scale_f32 v4, s[30:31], v2, v2, 1.0
	v_rcp_f32_e32 v7, v5
	v_rcp_f32_e32 v6, v4
	v_fma_f32 v9, -v5, v7, 1.0
	v_fma_f32 v8, -v4, v6, 1.0
	v_fmac_f32_e32 v7, v9, v7
	v_fmac_f32_e32 v6, v8, v6
	v_div_scale_f32 v9, vcc, 1.0, v3, 1.0
	v_mul_f32_e32 v11, v9, v7
	v_fma_f32 v13, -v5, v11, v9
	v_fmac_f32_e32 v11, v13, v7
	v_fma_f32 v5, -v5, v11, v9
	v_div_fmas_f32 v5, v5, v7, v11
	v_div_fixup_f32 v3, v5, v3, 1.0
	v_div_scale_f32 v8, vcc, 1.0, v2, 1.0
	v_mul_f32_e32 v10, v8, v6
	v_fma_f32 v12, -v4, v10, v8
	v_fmac_f32_e32 v10, v12, v6
	v_fma_f32 v4, -v4, v10, v8
	v_div_fmas_f32 v4, v4, v6, v10
	v_div_fixup_f32 v2, v4, v2, 1.0
	v_lshlrev_b32_e32 v14, 16, v151
	v_and_b32_e32 v15, 0xffff0000, v151
	v_lshlrev_b32_e32 v16, 16, v241
	v_and_b32_e32 v17, 0xffff0000, v241
	v_pk_fma_f32 v[2:3], v[2:3], v[14:15], v[16:17]
	s_nop 0
	v_cvt_pk_bf16_f32 v159, v2, v3
	global_load_dwordx4 v[198:201], v160, s[60:61]
	global_load_dwordx4 v[238:241], v19, s[62:63]
	s_add_u32 s60, s60, 0x51000
	s_addc_u32 s61, s61, 0
	s_add_u32 s62, s62, 0x10000
	s_addc_u32 s63, s63, 0
	global_store_dwordx4 v19, v[156:159], s[64:65]
	s_add_u32 s64, s64, 0x10000
	s_addc_u32 s65, s65, 0
	s_add_i32 s57, s57, 1
	s_cmp_eq_u32 s57, 3
	s_cselect_b32 s0, 0x510000, 0
	s_cselect_b32 s2, 0x100000, 0
	s_sub_u32 s60, s60, s0
	s_subb_u32 s61, s61, 0
	s_sub_u32 s62, s62, s2
	s_subb_u32 s63, s63, 0
	s_cmp_lt_u32 s57, 4
	s_cbranch_scc1 .Lmy_mergeN_loop
	s_branch .LBB0_888
; __device__ __forceinline__ float sigmoid_f(float x) { return 1.f / (1.f + __expf(-x)); }
; template <int NT, int BM, int BN, bool PLAIN, int NSTAGE, bool EPI_LDS>
; __device__ __forceinline__ void gemm_tile(const Params& p, const GemmDesc& g, bf16_t* lds, const int tid) {
;     ...
;     bf16_t* o = (bf16_t*)g.out;
;     const long ldo = (g.epi == E_PROJ) ? LDP : (g.epi == E_RELU2 ? 8192 : 2048);
;     const int gcol = COL_BG + g.auxi * 2048;
; #pragma unroll 4
;     for (int i = 0; i < NIT; ++i) {
;       const int id = tid + NT * i;
;       const int row = id / PPR, pc = id % PPR;
;       u32x4 v = *(const u32x4*)(ct + row * CST + pc * 8);
;       bf16_t* op = o + (long)(m0e + row) * ldo + n0e + pc * 8;
;       if (g.epi == E_MERGE0 || g.epi == E_MERGEN) {
;         const u32x4 gt = *(const u32x4*)(((bf16_t*)(p.ws + OFF_proj)) + (long)(m0e + row) * LDP + gcol + n0e + pc * 8);
;         u32x4 pv = u32x4{0u, 0u, 0u, 0u};
;         if (g.epi == E_MERGEN) pv = *(const u32x4*)op;
; #pragma unroll
;         for (int e = 0; e < 4; ++e) {
;           const float g0 = sigmoid_f(__uint_as_float(gt[e] << 16)), g1 = sigmoid_f(__uint_as_float(gt[e] & 0xffff0000u));
;           const float a0 = __uint_as_float(v[e] << 16), a1 = __uint_as_float(v[e] & 0xffff0000u);
;           const float p0 = __uint_as_float(pv[e] << 16), p1 = __uint_as_float(pv[e] & 0xffff0000u);
;           v[e] = pack2(p0 + g0 * a0, p1 + g1 * a1);
;         }
;       }
;       *(u32x4*)op = v;
;     }
.Lmy_plain:
	v_lshrrev_b32_e32 v2, 5, v224
	v_and_b32_e32 v3, 31, v224
	v_lshlrev_b32_e32 v3, 4, v3
	v_mad_u32_u24 v18, v2, s50, v3
	v_add_u32_e32 v17, 0x11000, v18
	v_add_u32_e32 v2, s23, v2
	s_lshl_b32 s0, s58, 1
	v_mul_lo_u32 v19, v2, s0
	v_add_u32_e32 v19, v19, v3
	s_lshl_b32 s0, s58, 5
	s_mov_b64 s[64:65], s[26:27]
	ds_read_b128 v[20:23], v18
	ds_read_b128 v[24:27], v18 offset:8704
	ds_read_b128 v[28:31], v18 offset:17408
	ds_read_b128 v[32:35], v18 offset:26112
	ds_read_b128 v[36:39], v18 offset:34816
	ds_read_b128 v[40:43], v18 offset:43520
	ds_read_b128 v[44:47], v18 offset:52224
	ds_read_b128 v[48:51], v18 offset:60928
	ds_read_b128 v[52:55], v17
	s_waitcnt lgkmcnt(8)
	global_store_dwordx4 v19, v[20:23], s[64:65]
	s_add_u32 s64, s64, s0
	s_addc_u32 s65, s65, 0
	ds_read_b128 v[56:59], v17 offset:8704
	s_waitcnt lgkmcnt(8)
	global_store_dwordx4 v19, v[24:27], s[64:65]
	s_add_u32 s64, s64, s0
	s_addc_u32 s65, s65, 0
	ds_read_b128 v[60:63], v17 offset:17408
	s_waitcnt lgkmcnt(8)
	global_store_dwordx4 v19, v[28:31], s[64:65]
	s_add_u32 s64, s64, s0
	s_addc_u32 s65, s65, 0
	ds_read_b128 v[64:67], v17 offset:26112
	s_waitcnt lgkmcnt(8)
	global_store_dwordx4 v19, v[32:35], s[64:65]
	s_add_u32 s64, s64, s0
	s_addc_u32 s65, s65, 0
	ds_read_b128 v[68:71], v17 offset:34816
	s_waitcnt lgkmcnt(8)
	global_store_dwordx4 v19, v[36:39], s[64:65]
	s_add_u32 s64, s64, s0
	s_addc_u32 s65, s65, 0
	ds_read_b128 v[72:75], v17 offset:43520
	s_waitcnt lgkmcnt(8)
	global_store_dwordx4 v19, v[40:43], s[64:65]
	s_add_u32 s64, s64, s0
	s_addc_u32 s65, s65, 0
	ds_read_b128 v[76:79], v17 offset:52224
	s_waitcnt lgkmcnt(8)
	global_store_dwordx4 v19, v[44:47], s[64:65]
	s_add_u32 s64, s64, s0
	s_addc_u32 s65, s65, 0
	ds_read_b128 v[80:83], v17 offset:60928
	s_waitcnt lgkmcnt(8)
	global_store_dwordx4 v19, v[48:51], s[64:65]
	s_add_u32 s64, s64, s0
	s_addc_u32 s65, s65, 0
	s_waitcnt lgkmcnt(7)
	global_store_dwordx4 v19, v[52:55], s[64:65]
	s_add_u32 s64, s64, s0
	s_addc_u32 s65, s65, 0
	s_waitcnt lgkmcnt(6)
	global_store_dwordx4 v19, v[56:59], s[64:65]
	s_add_u32 s64, s64, s0
	s_addc_u32 s65, s65, 0
	s_waitcnt lgkmcnt(5)
	global_store_dwordx4 v19, v[60:63], s[64:65]
	s_add_u32 s64, s64, s0
	s_addc_u32 s65, s65, 0
	s_waitcnt lgkmcnt(4)
	global_store_dwordx4 v19, v[64:67], s[64:65]
	s_add_u32 s64, s64, s0
	s_addc_u32 s65, s65, 0
	s_waitcnt lgkmcnt(3)
	global_store_dwordx4 v19, v[68:71], s[64:65]
	s_add_u32 s64, s64, s0
	s_addc_u32 s65, s65, 0
	s_waitcnt lgkmcnt(2)
	global_store_dwordx4 v19, v[72:75], s[64:65]
	s_add_u32 s64, s64, s0
	s_addc_u32 s65, s65, 0
	s_waitcnt lgkmcnt(1)
	global_store_dwordx4 v19, v[76:79], s[64:65]
	s_add_u32 s64, s64, s0
	s_addc_u32 s65, s65, 0
	s_waitcnt lgkmcnt(0)
	global_store_dwordx4 v19, v[80:83], s[64:65]
	s_add_u32 s64, s64, s0
	s_addc_u32 s65, s65, 0
	s_branch .LBB0_888
